# v62 + in-projection (proj) and softmax (P) output stores marked non-temporal: write-once streams should not displace the GEMM operand tiles in L2
# baseline (speedup 1.0000x reference)
; __device__ __forceinline__ unsigned cvt_pk_bf16(float lo, float hi) { unsigned r; asm volatile("v_cvt_pk_bf16_f32 %0, %1, %2" : "=v"(r) : "v"(lo), "v"(hi)); return r; }
; __device__ __forceinline__ f32x2 gelu_pk(f32x2 v) {
;     const f32x2 av = __builtin_elementwise_abs(v), d = av * 0.2316418882f + 1.0f;
;     f32x2 t; t.x = __builtin_amdgcn_rcpf(d.x); t.y = __builtin_amdgcn_rcpf(d.y);
;     f32x2 q = t * 0.5307027145f + (-0.7265760135f); q = q * t + 0.7107068705f; q = q * t + (-0.142248368f); q = q * t + 0.127414796f; q = q * t;
;     const f32x2 s = (v * v) * (-0.72134752044f);
;     f32x2 e; e.x = __builtin_amdgcn_exp2f(s.x); e.y = __builtin_amdgcn_exp2f(s.y);
;     const f32x2 m = v * (q * e), r = v - m;
;     f32x2 o; o.x = v.x < 0.f ? m.x : r.x; o.y = v.y < 0.f ? m.y : r.y; return o;
; }
;     __device__ __forceinline__ void operator()(const f32x4 (&acc)[2][2][4][2], const Unit& u, int wr, int wc, int fr, int fq) const {
;     ...
;             for (int m = 0; m < 4; ++m) { bf16_t* rowp = O + (size_t)(u.pm >> 5) * bgap + (size_t)u.pm * sm + (size_t)u.pn * sn + (size_t)(wr * 64 + fr + ai * HALF + m * 16) * ldc + wc * 32 + 8 * fq; const float sc = rs[ai][m]; float s1 = 0.f, s2 = 0.f;
; #pragma unroll
;                 for (int bj = 0; bj < 2; ++bj) { f32x4 v0 = acc[ai][bj][m][0] * sc, v1 = acc[ai][bj][m][1] * sc;
;                     if (do_gelu) { f32x2 a = gelu_pk((f32x2){v0[0], v0[1]}), b = gelu_pk((f32x2){v0[2], v0[3]}), c = gelu_pk((f32x2){v1[0], v1[1]}), d = gelu_pk((f32x2){v1[2], v1[3]});
;                         v0 = (f32x4){a.x, a.y, b.x, b.y}; v1 = (f32x4){c.x, c.y, d.x, d.y}; }
;                     if (do_stat) { s1 += ((v0[0] + v0[1]) + (v0[2] + v0[3])) + ((v1[0] + v1[1]) + (v1[2] + v1[3]));
;                         s2 += ((v0[0] * v0[0] + v0[1] * v0[1]) + (v0[2] * v0[2] + v0[3] * v0[3])) + ((v1[0] * v1[0] + v1[1] * v1[1]) + (v1[2] * v1[2] + v1[3] * v1[3])); }
;                     u32x4 w; w.x = cvt_pk_bf16(v0[0], v0[1]); w.y = cvt_pk_bf16(v0[2], v0[3]); w.z = cvt_pk_bf16(v1[0], v1[1]); w.w = cvt_pk_bf16(v1[2], v1[3]);
;                     *(u32x4*)(rowp + bj * HALF) = w; }
.LBB0_282:
	s_ashr_i32 s4, s6, 5
	s_mul_hi_i32 s5, s4, 0x1400000
	s_mul_i32 s4, s4, 0x1400000
	s_add_u32 s4, s12, s4
	s_addc_u32 s5, s13, s5
	s_mul_hi_i32 s9, s6, 0xc0000
	s_mul_i32 s6, s6, 0xc0000
	s_add_u32 s6, s4, s6
	s_addc_u32 s9, s5, s9
	s_ashr_i32 s61, s60, 31
	s_lshl_b64 s[4:5], s[60:61], 9
	s_add_u32 s16, s6, s4
	s_addc_u32 s17, s9, s5
	v_lshl_add_u64 v[174:175], s[16:17], 0, v[136:137]
	s_lshl_b32 s86, s47, 1
	v_cvt_pk_bf16_f32 v124, v124, v125
	v_cvt_pk_bf16_f32 v125, v126, v127
	v_cvt_pk_bf16_f32 v126, v172, v173
	v_cvt_pk_bf16_f32 v127, v122, v123
	v_mov_b32_e32 v122, v170
	v_mov_b32_e32 v123, v170
	v_mov_b32_e32 v171, v170
	v_lshl_add_u64 v[174:175], v[174:175], 0, s[86:87]
	v_pk_mul_f32 v[118:119], v[118:119], v[122:123]
	v_pk_mul_f32 v[114:115], v[114:115], v[122:123]
	v_cndmask_b32_e64 v122, 0, 1, s[0:1]
	v_lshl_add_u64 v[174:175], v[174:175], 0, v[192:193]
	v_pk_mul_f32 v[116:117], v[116:117], v[170:171]
	v_cmp_ne_u32_e64 s[42:43], 1, v122
	s_andn2_b64 vcc, exec, s[0:1]
	v_pk_mul_f32 v[122:123], v[112:113], v[170:171]
	global_store_dwordx4 v[174:175], v[124:127], off nt
	s_cbranch_vccnz .LBB0_284
	v_and_b32_e32 v113, 0x7fffffff, v117
	v_and_b32_e32 v112, 0x7fffffff, v116
	v_pk_fma_f32 v[112:113], v[112:113], s[28:29], 1.0 op_sel_hi:[1,0,0]
	s_mov_b32 s0, 0xbf3a00e3
	v_rcp_f32_e32 v124, v112
	v_rcp_f32_e32 v125, v113
	v_mov_b64_e32 v[112:113], s[0:1]
	v_pk_mul_f32 v[170:171], v[116:117], v[116:117]
	s_mov_b32 s0, 0xbf38aa3b
	v_pk_fma_f32 v[126:127], v[124:125], s[30:31], v[112:113] op_sel_hi:[1,0,0]
	v_pk_mul_f32 v[170:171], v[170:171], s[0:1] op_sel_hi:[1,0]
	v_pk_fma_f32 v[126:127], v[124:125], v[126:127], s[36:37] op_sel_hi:[1,1,0]
	v_exp_f32_e32 v170, v170
	v_exp_f32_e32 v171, v171
	v_pk_fma_f32 v[126:127], v[124:125], v[126:127], s[80:81] op_sel_hi:[1,1,0]
	v_cmp_gt_f32_e32 vcc, 0, v116
	v_pk_fma_f32 v[126:127], v[124:125], v[126:127], s[64:65] op_sel_hi:[1,1,0]
	s_nop 0
	v_pk_mul_f32 v[124:125], v[124:125], v[126:127]
	v_pk_mul_f32 v[126:127], v[118:119], v[118:119]
	v_pk_mul_f32 v[124:125], v[170:171], v[124:125]
	v_pk_mul_f32 v[126:127], v[126:127], s[0:1] op_sel_hi:[1,0]
	v_pk_mul_f32 v[170:171], v[116:117], v[124:125]
	v_pk_fma_f32 v[124:125], v[116:117], v[124:125], v[116:117] neg_lo:[1,0,0] neg_hi:[1,0,0]
	v_exp_f32_e32 v126, v126
	v_cndmask_b32_e32 v116, v124, v170, vcc
	v_cmp_gt_f32_e32 vcc, 0, v117
	v_and_b32_e32 v124, 0x7fffffff, v118
	v_exp_f32_e32 v127, v127
	v_cndmask_b32_e32 v117, v125, v171, vcc
	v_and_b32_e32 v125, 0x7fffffff, v119
	v_pk_fma_f32 v[124:125], v[124:125], s[28:29], 1.0 op_sel_hi:[1,0,0]
	v_cmp_gt_f32_e32 vcc, 0, v118
	v_rcp_f32_e32 v124, v124
	v_rcp_f32_e32 v125, v125
	s_nop 0
	v_pk_fma_f32 v[170:171], v[124:125], s[30:31], v[112:113] op_sel_hi:[1,0,0]
	s_nop 0
	v_pk_fma_f32 v[170:171], v[124:125], v[170:171], s[36:37] op_sel_hi:[1,1,0]
	s_nop 0
	v_pk_fma_f32 v[170:171], v[124:125], v[170:171], s[80:81] op_sel_hi:[1,1,0]
	s_nop 0
	v_pk_fma_f32 v[170:171], v[124:125], v[170:171], s[64:65] op_sel_hi:[1,1,0]
	s_nop 0
	v_pk_mul_f32 v[124:125], v[124:125], v[170:171]
	v_pk_mul_f32 v[170:171], v[122:123], v[122:123]
	v_pk_mul_f32 v[124:125], v[126:127], v[124:125]
	v_pk_mul_f32 v[170:171], v[170:171], s[0:1] op_sel_hi:[1,0]
	v_pk_mul_f32 v[126:127], v[118:119], v[124:125]
	v_pk_fma_f32 v[124:125], v[118:119], v[124:125], v[118:119] neg_lo:[1,0,0] neg_hi:[1,0,0]
	v_exp_f32_e32 v170, v170
	v_cndmask_b32_e32 v118, v124, v126, vcc
	v_cmp_gt_f32_e32 vcc, 0, v119
	v_and_b32_e32 v124, 0x7fffffff, v122
	v_exp_f32_e32 v171, v171
	v_cndmask_b32_e32 v119, v125, v127, vcc
	v_and_b32_e32 v125, 0x7fffffff, v123
	v_pk_fma_f32 v[124:125], v[124:125], s[28:29], 1.0 op_sel_hi:[1,0,0]
	v_cmp_gt_f32_e32 vcc, 0, v122
	v_rcp_f32_e32 v124, v124
	v_rcp_f32_e32 v125, v125
	s_nop 0
	v_pk_fma_f32 v[126:127], v[124:125], s[30:31], v[112:113] op_sel_hi:[1,0,0]
	s_nop 0
	v_pk_fma_f32 v[126:127], v[124:125], v[126:127], s[36:37] op_sel_hi:[1,1,0]
	s_nop 0
	v_pk_fma_f32 v[126:127], v[124:125], v[126:127], s[80:81] op_sel_hi:[1,1,0]
	s_nop 0
	v_pk_fma_f32 v[126:127], v[124:125], v[126:127], s[64:65] op_sel_hi:[1,1,0]
	s_nop 0
	v_pk_mul_f32 v[124:125], v[124:125], v[126:127]
	v_pk_mul_f32 v[126:127], v[114:115], v[114:115]
	v_pk_mul_f32 v[124:125], v[170:171], v[124:125]
	s_nop 0
	v_pk_mul_f32 v[170:171], v[122:123], v[124:125]
	v_pk_fma_f32 v[124:125], v[122:123], v[124:125], v[122:123] neg_lo:[1,0,0] neg_hi:[1,0,0]
	s_nop 0
	v_cndmask_b32_e32 v122, v124, v170, vcc
	v_cmp_gt_f32_e32 vcc, 0, v123
	v_and_b32_e32 v124, 0x7fffffff, v114
	s_nop 0
	v_cndmask_b32_e32 v123, v125, v171, vcc
	v_and_b32_e32 v125, 0x7fffffff, v115
	v_pk_fma_f32 v[124:125], v[124:125], s[28:29], 1.0 op_sel_hi:[1,0,0]
	v_cmp_gt_f32_e32 vcc, 0, v114
	v_rcp_f32_e32 v124, v124
	v_rcp_f32_e32 v125, v125
	s_nop 0
	v_pk_fma_f32 v[112:113], v[124:125], s[30:31], v[112:113] op_sel_hi:[1,0,0]
	s_nop 0
	v_pk_fma_f32 v[112:113], v[124:125], v[112:113], s[36:37] op_sel_hi:[1,1,0]
	s_nop 0
	v_pk_fma_f32 v[112:113], v[124:125], v[112:113], s[80:81] op_sel_hi:[1,1,0]
	s_nop 0
	v_pk_fma_f32 v[112:113], v[124:125], v[112:113], s[64:65] op_sel_hi:[1,1,0]
	s_nop 0
	v_pk_mul_f32 v[112:113], v[124:125], v[112:113]
	v_pk_mul_f32 v[124:125], v[126:127], s[0:1] op_sel_hi:[1,0]
	s_nop 0
	v_exp_f32_e32 v124, v124
	v_exp_f32_e32 v125, v125
	s_nop 0
	v_pk_mul_f32 v[112:113], v[124:125], v[112:113]
	s_nop 0
	v_pk_mul_f32 v[124:125], v[114:115], v[112:113]
	v_pk_fma_f32 v[112:113], v[114:115], v[112:113], v[114:115] neg_lo:[1,0,0] neg_hi:[1,0,0]
	s_nop 0
	v_cndmask_b32_e32 v114, v112, v124, vcc
	v_cmp_gt_f32_e32 vcc, 0, v115
	s_nop 1
	v_cndmask_b32_e32 v115, v113, v125, vcc

; __device__ __forceinline__ unsigned cvt_pk_bf16(float lo, float hi) { unsigned r; asm volatile("v_cvt_pk_bf16_f32 %0, %1, %2" : "=v"(r) : "v"(lo), "v"(hi)); return r; }
;     __device__ __forceinline__ void operator()(const f32x4 (&acc)[2][2][4][2], const Unit& u, int wr, int wc, int fr, int fq) const {
;     ...
;                     u32x4 w; w.x = cvt_pk_bf16(v0[0], v0[1]); w.y = cvt_pk_bf16(v0[2], v0[3]); w.z = cvt_pk_bf16(v1[0], v1[1]); w.w = cvt_pk_bf16(v1[2], v1[3]);
;                     *(u32x4*)(rowp + bj * HALF) = w; }
;                 if (do_stat) { s1 += __shfl_xor(s1, 16); s1 += __shfl_xor(s1, 32); s2 += __shfl_xor(s2, 16); s2 += __shfl_xor(s2, 32);
;                     if (fq == 0) *(f32x2*)(vstat + ((size_t)(row0 + ai * HALF + m * 16) * 8 + (u.pn - vstat_pn0) * 4 + wc) * 2) = (f32x2){s1, s2}; }
.LBB0_288:
	v_cndmask_b32_e64 v113, 0, 1, s[92:93]
	v_cvt_pk_bf16_f32 v116, v116, v117
	v_cvt_pk_bf16_f32 v117, v118, v119
	v_cvt_pk_bf16_f32 v118, v122, v123
	v_cvt_pk_bf16_f32 v119, v114, v115
	v_cmp_ne_u32_e64 s[44:45], 1, v113
	v_and_b32_e32 v113, 64, v252
	v_or_b32_e32 v112, s8, v176
	global_store_dwordx4 v[174:175], v[116:119], off offset:256 nt
	s_andn2_b64 vcc, exec, s[92:93]
	v_xor_b32_e32 v120, 16, v252
	v_xor_b32_e32 v118, 32, v252
	v_add_u32_e32 v119, 64, v113
	s_cbranch_vccnz .LBB0_292
	v_cmp_lt_i32_e32 vcc, v120, v119
	s_nop 1
	v_cndmask_b32_e32 v113, v252, v120, vcc
	v_lshlrev_b32_e32 v113, 2, v113
	ds_bpermute_b32 v114, v113, v124
	ds_bpermute_b32 v115, v113, v125
	v_cmp_lt_i32_e32 vcc, v118, v119
	s_waitcnt lgkmcnt(0)
	v_pk_add_f32 v[114:115], v[124:125], v[114:115]
	v_cndmask_b32_e32 v113, v252, v118, vcc
	v_lshlrev_b32_e32 v113, 2, v113
	ds_bpermute_b32 v116, v113, v114
	ds_bpermute_b32 v117, v113, v115
	s_and_saveexec_b64 s[0:1], s[38:39]
	s_cbranch_execz .LBB0_291
	s_lshl_b32 s4, s60, 2
	s_add_i32 s4, s4, -16
	s_waitcnt lgkmcnt(0)
	v_pk_add_f32 v[114:115], v[114:115], v[116:117]
	v_ashrrev_i32_e32 v113, 31, v112
	v_mov_b32_e32 v116, s4
	v_mov_b32_e32 v117, v193
	v_lshl_add_u64 v[116:117], v[112:113], 3, v[116:117]
	v_or_b32_e32 v116, s83, v116
	v_lshl_add_u64 v[116:117], v[116:117], 3, s[20:21]
	global_store_dwordx2 v[116:117], v[114:115], off

; __device__ __forceinline__ unsigned cvt_pk_bf16(float lo, float hi) { unsigned r; asm volatile("v_cvt_pk_bf16_f32 %0, %1, %2" : "=v"(r) : "v"(lo), "v"(hi)); return r; }
; __device__ __forceinline__ f32x2 gelu_pk(f32x2 v) {
;     const f32x2 av = __builtin_elementwise_abs(v), d = av * 0.2316418882f + 1.0f;
;     f32x2 t; t.x = __builtin_amdgcn_rcpf(d.x); t.y = __builtin_amdgcn_rcpf(d.y);
;     f32x2 q = t * 0.5307027145f + (-0.7265760135f); q = q * t + 0.7107068705f; q = q * t + (-0.142248368f); q = q * t + 0.127414796f; q = q * t;
;     const f32x2 s = (v * v) * (-0.72134752044f);
;     f32x2 e; e.x = __builtin_amdgcn_exp2f(s.x); e.y = __builtin_amdgcn_exp2f(s.y);
;     const f32x2 m = v * (q * e), r = v - m;
;     f32x2 o; o.x = v.x < 0.f ? m.x : r.x; o.y = v.y < 0.f ? m.y : r.y; return o;
; }
;     __device__ __forceinline__ void operator()(const f32x4 (&acc)[2][2][4][2], const Unit& u, int wr, int wc, int fr, int fq) const {
;     ...
;             for (int m = 0; m < 4; ++m) { bf16_t* rowp = O + (size_t)(u.pm >> 5) * bgap + (size_t)u.pm * sm + (size_t)u.pn * sn + (size_t)(wr * 64 + fr + ai * HALF + m * 16) * ldc + wc * 32 + 8 * fq; const float sc = rs[ai][m]; float s1 = 0.f, s2 = 0.f;
; #pragma unroll
;                 for (int bj = 0; bj < 2; ++bj) { f32x4 v0 = acc[ai][bj][m][0] * sc, v1 = acc[ai][bj][m][1] * sc;
;                     if (do_gelu) { f32x2 a = gelu_pk((f32x2){v0[0], v0[1]}), b = gelu_pk((f32x2){v0[2], v0[3]}), c = gelu_pk((f32x2){v1[0], v1[1]}), d = gelu_pk((f32x2){v1[2], v1[3]});
;                         v0 = (f32x4){a.x, a.y, b.x, b.y}; v1 = (f32x4){c.x, c.y, d.x, d.y}; }
;                     if (do_stat) { s1 += ((v0[0] + v0[1]) + (v0[2] + v0[3])) + ((v1[0] + v1[1]) + (v1[2] + v1[3]));
;                         s2 += ((v0[0] * v0[0] + v0[1] * v0[1]) + (v0[2] * v0[2] + v0[3] * v0[3])) + ((v1[0] * v1[0] + v1[1] * v1[1]) + (v1[2] * v1[2] + v1[3] * v1[3])); }
;                     u32x4 w; w.x = cvt_pk_bf16(v0[0], v0[1]); w.y = cvt_pk_bf16(v0[2], v0[3]); w.z = cvt_pk_bf16(v1[0], v1[1]); w.w = cvt_pk_bf16(v1[2], v1[3]);
;                     *(u32x4*)(rowp + bj * HALF) = w; }
.LBB0_298:
	v_lshl_add_u64 v[106:107], s[16:17], 0, v[138:139]
	v_lshl_add_u64 v[106:107], v[106:107], 0, s[86:87]
	v_lshl_add_u64 v[106:107], v[106:107], 0, v[192:193]
	v_cvt_pk_bf16_f32 v108, v108, v109
	v_cvt_pk_bf16_f32 v109, v110, v111
	v_mov_b32_e32 v169, v168
	v_cvt_pk_bf16_f32 v110, v116, v117
	v_cvt_pk_bf16_f32 v111, v114, v115
	global_store_dwordx4 v[106:107], v[108:111], off nt
	v_pk_mul_f32 v[100:101], v[100:101], v[168:169]
	s_and_b64 vcc, exec, s[42:43]
	v_mov_b32_e32 v108, v168
	v_mov_b32_e32 v109, v168
	v_pk_mul_f32 v[102:103], v[102:103], v[108:109]
	v_pk_mul_f32 v[98:99], v[98:99], v[108:109]
	v_pk_mul_f32 v[96:97], v[96:97], v[168:169]
	s_cbranch_vccnz .LBB0_300
	v_and_b32_e32 v109, 0x7fffffff, v101
	v_and_b32_e32 v108, 0x7fffffff, v100
	v_pk_fma_f32 v[108:109], v[108:109], s[28:29], 1.0 op_sel_hi:[1,0,0]
	s_mov_b32 s0, 0xbf3a00e3
	v_rcp_f32_e32 v110, v108
	v_rcp_f32_e32 v111, v109
	v_mov_b64_e32 v[108:109], s[0:1]
	v_pk_mul_f32 v[116:117], v[100:101], v[100:101]
	s_mov_b32 s0, 0xbf38aa3b
	v_pk_fma_f32 v[114:115], v[110:111], s[30:31], v[108:109] op_sel_hi:[1,0,0]
	v_pk_mul_f32 v[116:117], v[116:117], s[0:1] op_sel_hi:[1,0]
	v_pk_fma_f32 v[114:115], v[110:111], v[114:115], s[36:37] op_sel_hi:[1,1,0]
	v_exp_f32_e32 v116, v116
	v_exp_f32_e32 v117, v117
	v_pk_fma_f32 v[114:115], v[110:111], v[114:115], s[80:81] op_sel_hi:[1,1,0]
	v_cmp_gt_f32_e32 vcc, 0, v100
	v_pk_fma_f32 v[114:115], v[110:111], v[114:115], s[64:65] op_sel_hi:[1,1,0]
	s_nop 0
	v_pk_mul_f32 v[110:111], v[110:111], v[114:115]
	v_pk_mul_f32 v[114:115], v[102:103], v[102:103]
	v_pk_mul_f32 v[110:111], v[116:117], v[110:111]
	v_pk_mul_f32 v[114:115], v[114:115], s[0:1] op_sel_hi:[1,0]
	v_pk_mul_f32 v[116:117], v[100:101], v[110:111]
	v_pk_fma_f32 v[110:111], v[100:101], v[110:111], v[100:101] neg_lo:[1,0,0] neg_hi:[1,0,0]
	v_exp_f32_e32 v114, v114
	v_cndmask_b32_e32 v100, v110, v116, vcc
	v_cmp_gt_f32_e32 vcc, 0, v101
	v_and_b32_e32 v110, 0x7fffffff, v102
	v_exp_f32_e32 v115, v115
	v_cndmask_b32_e32 v101, v111, v117, vcc
	v_and_b32_e32 v111, 0x7fffffff, v103
	v_pk_fma_f32 v[110:111], v[110:111], s[28:29], 1.0 op_sel_hi:[1,0,0]
	v_cmp_gt_f32_e32 vcc, 0, v102
	v_rcp_f32_e32 v110, v110
	v_rcp_f32_e32 v111, v111
	s_nop 0
	v_pk_fma_f32 v[116:117], v[110:111], s[30:31], v[108:109] op_sel_hi:[1,0,0]
	s_nop 0
	v_pk_fma_f32 v[116:117], v[110:111], v[116:117], s[36:37] op_sel_hi:[1,1,0]
	s_nop 0
	v_pk_fma_f32 v[116:117], v[110:111], v[116:117], s[80:81] op_sel_hi:[1,1,0]
	s_nop 0
	v_pk_fma_f32 v[116:117], v[110:111], v[116:117], s[64:65] op_sel_hi:[1,1,0]
	s_nop 0
	v_pk_mul_f32 v[110:111], v[110:111], v[116:117]
	v_pk_mul_f32 v[116:117], v[96:97], v[96:97]
	v_pk_mul_f32 v[110:111], v[114:115], v[110:111]
	v_pk_mul_f32 v[116:117], v[116:117], s[0:1] op_sel_hi:[1,0]
	v_pk_mul_f32 v[114:115], v[102:103], v[110:111]
	v_pk_fma_f32 v[110:111], v[102:103], v[110:111], v[102:103] neg_lo:[1,0,0] neg_hi:[1,0,0]
	v_exp_f32_e32 v116, v116
	v_cndmask_b32_e32 v102, v110, v114, vcc
	v_cmp_gt_f32_e32 vcc, 0, v103
	v_and_b32_e32 v110, 0x7fffffff, v96
	v_exp_f32_e32 v117, v117
	v_cndmask_b32_e32 v103, v111, v115, vcc
	v_and_b32_e32 v111, 0x7fffffff, v97
	v_pk_fma_f32 v[110:111], v[110:111], s[28:29], 1.0 op_sel_hi:[1,0,0]
	v_cmp_gt_f32_e32 vcc, 0, v96
	v_rcp_f32_e32 v110, v110
	v_rcp_f32_e32 v111, v111
	s_nop 0
	v_pk_fma_f32 v[114:115], v[110:111], s[30:31], v[108:109] op_sel_hi:[1,0,0]
	s_nop 0
	v_pk_fma_f32 v[114:115], v[110:111], v[114:115], s[36:37] op_sel_hi:[1,1,0]
	s_nop 0
	v_pk_fma_f32 v[114:115], v[110:111], v[114:115], s[80:81] op_sel_hi:[1,1,0]
	s_nop 0
	v_pk_fma_f32 v[114:115], v[110:111], v[114:115], s[64:65] op_sel_hi:[1,1,0]
	s_nop 0
	v_pk_mul_f32 v[110:111], v[110:111], v[114:115]
	v_pk_mul_f32 v[114:115], v[98:99], v[98:99]
	v_pk_mul_f32 v[110:111], v[116:117], v[110:111]
	s_nop 0
	v_pk_mul_f32 v[116:117], v[96:97], v[110:111]
	v_pk_fma_f32 v[110:111], v[96:97], v[110:111], v[96:97] neg_lo:[1,0,0] neg_hi:[1,0,0]
	s_nop 0
	v_cndmask_b32_e32 v96, v110, v116, vcc
	v_cmp_gt_f32_e32 vcc, 0, v97
	v_and_b32_e32 v110, 0x7fffffff, v98
	s_nop 0
	v_cndmask_b32_e32 v97, v111, v117, vcc
	v_and_b32_e32 v111, 0x7fffffff, v99
	v_pk_fma_f32 v[110:111], v[110:111], s[28:29], 1.0 op_sel_hi:[1,0,0]
	v_cmp_gt_f32_e32 vcc, 0, v98
	v_rcp_f32_e32 v110, v110
	v_rcp_f32_e32 v111, v111
	s_nop 0
	v_pk_fma_f32 v[108:109], v[110:111], s[30:31], v[108:109] op_sel_hi:[1,0,0]
	s_nop 0
	v_pk_fma_f32 v[108:109], v[110:111], v[108:109], s[36:37] op_sel_hi:[1,1,0]
	s_nop 0
	v_pk_fma_f32 v[108:109], v[110:111], v[108:109], s[80:81] op_sel_hi:[1,1,0]
	s_nop 0
	v_pk_fma_f32 v[108:109], v[110:111], v[108:109], s[64:65] op_sel_hi:[1,1,0]
	s_nop 0
	v_pk_mul_f32 v[108:109], v[110:111], v[108:109]
	v_pk_mul_f32 v[110:111], v[114:115], s[0:1] op_sel_hi:[1,0]
	s_nop 0
	v_exp_f32_e32 v110, v110
	v_exp_f32_e32 v111, v111
	s_nop 0
	v_pk_mul_f32 v[108:109], v[110:111], v[108:109]
	s_nop 0
	v_pk_mul_f32 v[110:111], v[98:99], v[108:109]
	v_pk_fma_f32 v[108:109], v[98:99], v[108:109], v[98:99] neg_lo:[1,0,0] neg_hi:[1,0,0]
	s_nop 0
	v_cndmask_b32_e32 v98, v108, v110, vcc
	v_cmp_gt_f32_e32 vcc, 0, v99
	s_nop 1
	v_cndmask_b32_e32 v99, v109, v111, vcc

; __device__ __forceinline__ unsigned cvt_pk_bf16(float lo, float hi) { unsigned r; asm volatile("v_cvt_pk_bf16_f32 %0, %1, %2" : "=v"(r) : "v"(lo), "v"(hi)); return r; }
;     __device__ __forceinline__ void operator()(const f32x4 (&acc)[2][2][4][2], const Unit& u, int wr, int wc, int fr, int fq) const {
;     ...
;                     u32x4 w; w.x = cvt_pk_bf16(v0[0], v0[1]); w.y = cvt_pk_bf16(v0[2], v0[3]); w.z = cvt_pk_bf16(v1[0], v1[1]); w.w = cvt_pk_bf16(v1[2], v1[3]);
;                     *(u32x4*)(rowp + bj * HALF) = w; }
;                 if (do_stat) { s1 += __shfl_xor(s1, 16); s1 += __shfl_xor(s1, 32); s2 += __shfl_xor(s2, 16); s2 += __shfl_xor(s2, 32);
;                     if (fq == 0) *(f32x2*)(vstat + ((size_t)(row0 + ai * HALF + m * 16) * 8 + (u.pn - vstat_pn0) * 4 + wc) * 2) = (f32x2){s1, s2}; }
.LBB0_304:
	s_and_b64 vcc, exec, s[44:45]
	v_cvt_pk_bf16_f32 v100, v100, v101
	v_cvt_pk_bf16_f32 v101, v102, v103
	v_cvt_pk_bf16_f32 v102, v96, v97
	v_cvt_pk_bf16_f32 v103, v98, v99
	global_store_dwordx4 v[106:107], v[100:103], off offset:256 nt
	s_cbranch_vccnz .LBB0_308
	v_cmp_lt_i32_e32 vcc, v120, v119
	s_nop 1
	v_cndmask_b32_e32 v96, v252, v120, vcc
	v_lshlrev_b32_e32 v97, 2, v96
	ds_bpermute_b32 v96, v97, v108
	ds_bpermute_b32 v97, v97, v109
	v_cmp_lt_i32_e32 vcc, v118, v119
	s_waitcnt lgkmcnt(0)
	v_pk_add_f32 v[96:97], v[108:109], v[96:97]
	v_cndmask_b32_e32 v98, v252, v118, vcc
	v_lshlrev_b32_e32 v99, 2, v98
	ds_bpermute_b32 v98, v99, v96
	ds_bpermute_b32 v99, v99, v97
	s_and_saveexec_b64 s[0:1], s[38:39]
	s_cbranch_execz .LBB0_307
	s_lshl_b32 s4, s60, 2
	s_waitcnt lgkmcnt(0)
	v_pk_add_f32 v[96:97], v[96:97], v[98:99]
	v_or_b32_e32 v98, 16, v112
	s_add_i32 s4, s4, -16
	v_ashrrev_i32_e32 v99, 31, v98
	v_mov_b32_e32 v100, s4
	v_mov_b32_e32 v101, v193
	v_lshl_add_u64 v[98:99], v[98:99], 3, v[100:101]
	v_or_b32_e32 v98, s83, v98
	v_lshl_add_u64 v[98:99], v[98:99], 3, s[20:21]
	global_store_dwordx2 v[98:99], v[96:97], off

; __device__ __forceinline__ unsigned cvt_pk_bf16(float lo, float hi) { unsigned r; asm volatile("v_cvt_pk_bf16_f32 %0, %1, %2" : "=v"(r) : "v"(lo), "v"(hi)); return r; }
; __device__ __forceinline__ f32x2 gelu_pk(f32x2 v) {
;     const f32x2 av = __builtin_elementwise_abs(v), d = av * 0.2316418882f + 1.0f;
;     f32x2 t; t.x = __builtin_amdgcn_rcpf(d.x); t.y = __builtin_amdgcn_rcpf(d.y);
;     f32x2 q = t * 0.5307027145f + (-0.7265760135f); q = q * t + 0.7107068705f; q = q * t + (-0.142248368f); q = q * t + 0.127414796f; q = q * t;
;     const f32x2 s = (v * v) * (-0.72134752044f);
;     f32x2 e; e.x = __builtin_amdgcn_exp2f(s.x); e.y = __builtin_amdgcn_exp2f(s.y);
;     const f32x2 m = v * (q * e), r = v - m;
;     f32x2 o; o.x = v.x < 0.f ? m.x : r.x; o.y = v.y < 0.f ? m.y : r.y; return o;
; }
;     __device__ __forceinline__ void operator()(const f32x4 (&acc)[2][2][4][2], const Unit& u, int wr, int wc, int fr, int fq) const {
;     ...
;             for (int m = 0; m < 4; ++m) { bf16_t* rowp = O + (size_t)(u.pm >> 5) * bgap + (size_t)u.pm * sm + (size_t)u.pn * sn + (size_t)(wr * 64 + fr + ai * HALF + m * 16) * ldc + wc * 32 + 8 * fq; const float sc = rs[ai][m]; float s1 = 0.f, s2 = 0.f;
; #pragma unroll
;                 for (int bj = 0; bj < 2; ++bj) { f32x4 v0 = acc[ai][bj][m][0] * sc, v1 = acc[ai][bj][m][1] * sc;
;                     if (do_gelu) { f32x2 a = gelu_pk((f32x2){v0[0], v0[1]}), b = gelu_pk((f32x2){v0[2], v0[3]}), c = gelu_pk((f32x2){v1[0], v1[1]}), d = gelu_pk((f32x2){v1[2], v1[3]});
;                         v0 = (f32x4){a.x, a.y, b.x, b.y}; v1 = (f32x4){c.x, c.y, d.x, d.y}; }
;                     if (do_stat) { s1 += ((v0[0] + v0[1]) + (v0[2] + v0[3])) + ((v1[0] + v1[1]) + (v1[2] + v1[3]));
;                         s2 += ((v0[0] * v0[0] + v0[1] * v0[1]) + (v0[2] * v0[2] + v0[3] * v0[3])) + ((v1[0] * v1[0] + v1[1] * v1[1]) + (v1[2] * v1[2] + v1[3] * v1[3])); }
;                     u32x4 w; w.x = cvt_pk_bf16(v0[0], v0[1]); w.y = cvt_pk_bf16(v0[2], v0[3]); w.z = cvt_pk_bf16(v1[0], v1[1]); w.w = cvt_pk_bf16(v1[2], v1[3]);
;                     *(u32x4*)(rowp + bj * HALF) = w; }
.LBB0_314:
	v_lshl_add_u64 v[90:91], s[16:17], 0, v[140:141]
	v_lshl_add_u64 v[90:91], v[90:91], 0, s[86:87]
	v_lshl_add_u64 v[90:91], v[90:91], 0, v[192:193]
	v_cvt_pk_bf16_f32 v92, v92, v93
	v_cvt_pk_bf16_f32 v93, v94, v95
	v_mov_b32_e32 v167, v166
	v_cvt_pk_bf16_f32 v94, v98, v99
	v_cvt_pk_bf16_f32 v95, v96, v97
	global_store_dwordx4 v[90:91], v[92:95], off nt
	v_pk_mul_f32 v[84:85], v[84:85], v[166:167]
	s_and_b64 vcc, exec, s[42:43]
	v_mov_b32_e32 v92, v166
	v_mov_b32_e32 v93, v166
	v_pk_mul_f32 v[86:87], v[86:87], v[92:93]
	v_pk_mul_f32 v[82:83], v[82:83], v[92:93]
	v_pk_mul_f32 v[80:81], v[80:81], v[166:167]
	s_cbranch_vccnz .LBB0_316
	v_and_b32_e32 v93, 0x7fffffff, v85
	v_and_b32_e32 v92, 0x7fffffff, v84
	v_pk_fma_f32 v[92:93], v[92:93], s[28:29], 1.0 op_sel_hi:[1,0,0]
	s_mov_b32 s0, 0xbf3a00e3
	v_rcp_f32_e32 v94, v92
	v_rcp_f32_e32 v95, v93
	v_mov_b64_e32 v[92:93], s[0:1]
	v_pk_mul_f32 v[98:99], v[84:85], v[84:85]
	s_mov_b32 s0, 0xbf38aa3b
	v_pk_fma_f32 v[96:97], v[94:95], s[30:31], v[92:93] op_sel_hi:[1,0,0]
	v_pk_mul_f32 v[98:99], v[98:99], s[0:1] op_sel_hi:[1,0]
	v_pk_fma_f32 v[96:97], v[94:95], v[96:97], s[36:37] op_sel_hi:[1,1,0]
	v_exp_f32_e32 v98, v98
	v_exp_f32_e32 v99, v99
	v_pk_fma_f32 v[96:97], v[94:95], v[96:97], s[80:81] op_sel_hi:[1,1,0]
	v_cmp_gt_f32_e32 vcc, 0, v84
	v_pk_fma_f32 v[96:97], v[94:95], v[96:97], s[64:65] op_sel_hi:[1,1,0]
	s_nop 0
	v_pk_mul_f32 v[94:95], v[94:95], v[96:97]
	v_pk_mul_f32 v[96:97], v[86:87], v[86:87]
	v_pk_mul_f32 v[94:95], v[98:99], v[94:95]
	v_pk_mul_f32 v[96:97], v[96:97], s[0:1] op_sel_hi:[1,0]
	v_pk_mul_f32 v[98:99], v[84:85], v[94:95]
	v_pk_fma_f32 v[94:95], v[84:85], v[94:95], v[84:85] neg_lo:[1,0,0] neg_hi:[1,0,0]
	v_exp_f32_e32 v96, v96
	v_cndmask_b32_e32 v84, v94, v98, vcc
	v_cmp_gt_f32_e32 vcc, 0, v85
	v_and_b32_e32 v94, 0x7fffffff, v86
	v_exp_f32_e32 v97, v97
	v_cndmask_b32_e32 v85, v95, v99, vcc
	v_and_b32_e32 v95, 0x7fffffff, v87
	v_pk_fma_f32 v[94:95], v[94:95], s[28:29], 1.0 op_sel_hi:[1,0,0]
	v_cmp_gt_f32_e32 vcc, 0, v86
	v_rcp_f32_e32 v94, v94
	v_rcp_f32_e32 v95, v95
	s_nop 0
	v_pk_fma_f32 v[98:99], v[94:95], s[30:31], v[92:93] op_sel_hi:[1,0,0]
	s_nop 0
	v_pk_fma_f32 v[98:99], v[94:95], v[98:99], s[36:37] op_sel_hi:[1,1,0]
	s_nop 0
	v_pk_fma_f32 v[98:99], v[94:95], v[98:99], s[80:81] op_sel_hi:[1,1,0]
	s_nop 0
	v_pk_fma_f32 v[98:99], v[94:95], v[98:99], s[64:65] op_sel_hi:[1,1,0]
	s_nop 0
	v_pk_mul_f32 v[94:95], v[94:95], v[98:99]
	v_pk_mul_f32 v[98:99], v[80:81], v[80:81]
	v_pk_mul_f32 v[94:95], v[96:97], v[94:95]
	v_pk_mul_f32 v[98:99], v[98:99], s[0:1] op_sel_hi:[1,0]
	v_pk_mul_f32 v[96:97], v[86:87], v[94:95]
	v_pk_fma_f32 v[94:95], v[86:87], v[94:95], v[86:87] neg_lo:[1,0,0] neg_hi:[1,0,0]
	v_exp_f32_e32 v98, v98
	v_cndmask_b32_e32 v86, v94, v96, vcc
	v_cmp_gt_f32_e32 vcc, 0, v87
	v_and_b32_e32 v94, 0x7fffffff, v80
	v_exp_f32_e32 v99, v99
	v_cndmask_b32_e32 v87, v95, v97, vcc
	v_and_b32_e32 v95, 0x7fffffff, v81
	v_pk_fma_f32 v[94:95], v[94:95], s[28:29], 1.0 op_sel_hi:[1,0,0]
	v_cmp_gt_f32_e32 vcc, 0, v80
	v_rcp_f32_e32 v94, v94
	v_rcp_f32_e32 v95, v95
	s_nop 0
	v_pk_fma_f32 v[96:97], v[94:95], s[30:31], v[92:93] op_sel_hi:[1,0,0]
	s_nop 0
	v_pk_fma_f32 v[96:97], v[94:95], v[96:97], s[36:37] op_sel_hi:[1,1,0]
	s_nop 0
	v_pk_fma_f32 v[96:97], v[94:95], v[96:97], s[80:81] op_sel_hi:[1,1,0]
	s_nop 0
	v_pk_fma_f32 v[96:97], v[94:95], v[96:97], s[64:65] op_sel_hi:[1,1,0]
	s_nop 0
	v_pk_mul_f32 v[94:95], v[94:95], v[96:97]
	v_pk_mul_f32 v[96:97], v[82:83], v[82:83]
	v_pk_mul_f32 v[94:95], v[98:99], v[94:95]
	s_nop 0
	v_pk_mul_f32 v[98:99], v[80:81], v[94:95]
	v_pk_fma_f32 v[94:95], v[80:81], v[94:95], v[80:81] neg_lo:[1,0,0] neg_hi:[1,0,0]
	s_nop 0
	v_cndmask_b32_e32 v80, v94, v98, vcc
	v_cmp_gt_f32_e32 vcc, 0, v81
	v_and_b32_e32 v94, 0x7fffffff, v82
	s_nop 0
	v_cndmask_b32_e32 v81, v95, v99, vcc
	v_and_b32_e32 v95, 0x7fffffff, v83
	v_pk_fma_f32 v[94:95], v[94:95], s[28:29], 1.0 op_sel_hi:[1,0,0]
	v_cmp_gt_f32_e32 vcc, 0, v82
	v_rcp_f32_e32 v94, v94
	v_rcp_f32_e32 v95, v95
	s_nop 0
	v_pk_fma_f32 v[92:93], v[94:95], s[30:31], v[92:93] op_sel_hi:[1,0,0]
	s_nop 0
	v_pk_fma_f32 v[92:93], v[94:95], v[92:93], s[36:37] op_sel_hi:[1,1,0]
	s_nop 0
	v_pk_fma_f32 v[92:93], v[94:95], v[92:93], s[80:81] op_sel_hi:[1,1,0]
	s_nop 0
	v_pk_fma_f32 v[92:93], v[94:95], v[92:93], s[64:65] op_sel_hi:[1,1,0]
	s_nop 0
	v_pk_mul_f32 v[92:93], v[94:95], v[92:93]
	v_pk_mul_f32 v[94:95], v[96:97], s[0:1] op_sel_hi:[1,0]
	s_nop 0
	v_exp_f32_e32 v94, v94
	v_exp_f32_e32 v95, v95
	s_nop 0
	v_pk_mul_f32 v[92:93], v[94:95], v[92:93]
	s_nop 0
	v_pk_mul_f32 v[94:95], v[82:83], v[92:93]
	v_pk_fma_f32 v[92:93], v[82:83], v[92:93], v[82:83] neg_lo:[1,0,0] neg_hi:[1,0,0]
	s_nop 0
	v_cndmask_b32_e32 v82, v92, v94, vcc
	v_cmp_gt_f32_e32 vcc, 0, v83
	s_nop 1
	v_cndmask_b32_e32 v83, v93, v95, vcc

; __device__ __forceinline__ unsigned cvt_pk_bf16(float lo, float hi) { unsigned r; asm volatile("v_cvt_pk_bf16_f32 %0, %1, %2" : "=v"(r) : "v"(lo), "v"(hi)); return r; }
;     __device__ __forceinline__ void operator()(const f32x4 (&acc)[2][2][4][2], const Unit& u, int wr, int wc, int fr, int fq) const {
;     ...
;                     u32x4 w; w.x = cvt_pk_bf16(v0[0], v0[1]); w.y = cvt_pk_bf16(v0[2], v0[3]); w.z = cvt_pk_bf16(v1[0], v1[1]); w.w = cvt_pk_bf16(v1[2], v1[3]);
;                     *(u32x4*)(rowp + bj * HALF) = w; }
;                 if (do_stat) { s1 += __shfl_xor(s1, 16); s1 += __shfl_xor(s1, 32); s2 += __shfl_xor(s2, 16); s2 += __shfl_xor(s2, 32);
;                     if (fq == 0) *(f32x2*)(vstat + ((size_t)(row0 + ai * HALF + m * 16) * 8 + (u.pn - vstat_pn0) * 4 + wc) * 2) = (f32x2){s1, s2}; }
.LBB0_320:
	s_and_b64 vcc, exec, s[44:45]
	v_cvt_pk_bf16_f32 v84, v84, v85
	v_cvt_pk_bf16_f32 v85, v86, v87
	v_cvt_pk_bf16_f32 v86, v80, v81
	v_cvt_pk_bf16_f32 v87, v82, v83
	global_store_dwordx4 v[90:91], v[84:87], off offset:256 nt
	s_cbranch_vccnz .LBB0_324
	v_cmp_lt_i32_e32 vcc, v120, v119
	s_nop 1
	v_cndmask_b32_e32 v80, v252, v120, vcc
	v_lshlrev_b32_e32 v81, 2, v80
	ds_bpermute_b32 v80, v81, v92
	ds_bpermute_b32 v81, v81, v93
	v_cmp_lt_i32_e32 vcc, v118, v119
	s_waitcnt lgkmcnt(0)
	v_pk_add_f32 v[80:81], v[92:93], v[80:81]
	v_cndmask_b32_e32 v82, v252, v118, vcc
	v_lshlrev_b32_e32 v83, 2, v82
	ds_bpermute_b32 v82, v83, v80
	ds_bpermute_b32 v83, v83, v81
	s_and_saveexec_b64 s[0:1], s[38:39]
	s_cbranch_execz .LBB0_323
	s_lshl_b32 s4, s60, 2
	s_waitcnt lgkmcnt(0)
	v_pk_add_f32 v[80:81], v[80:81], v[82:83]
	v_or_b32_e32 v82, 32, v112
	s_add_i32 s4, s4, -16
	v_ashrrev_i32_e32 v83, 31, v82
	v_mov_b32_e32 v84, s4
	v_mov_b32_e32 v85, v193
	v_lshl_add_u64 v[82:83], v[82:83], 3, v[84:85]
	v_or_b32_e32 v82, s83, v82
	v_lshl_add_u64 v[82:83], v[82:83], 3, s[20:21]
	global_store_dwordx2 v[82:83], v[80:81], off

; __device__ __forceinline__ unsigned cvt_pk_bf16(float lo, float hi) { unsigned r; asm volatile("v_cvt_pk_bf16_f32 %0, %1, %2" : "=v"(r) : "v"(lo), "v"(hi)); return r; }
; __device__ __forceinline__ f32x2 gelu_pk(f32x2 v) {
;     const f32x2 av = __builtin_elementwise_abs(v), d = av * 0.2316418882f + 1.0f;
;     f32x2 t; t.x = __builtin_amdgcn_rcpf(d.x); t.y = __builtin_amdgcn_rcpf(d.y);
;     f32x2 q = t * 0.5307027145f + (-0.7265760135f); q = q * t + 0.7107068705f; q = q * t + (-0.142248368f); q = q * t + 0.127414796f; q = q * t;
;     const f32x2 s = (v * v) * (-0.72134752044f);
;     f32x2 e; e.x = __builtin_amdgcn_exp2f(s.x); e.y = __builtin_amdgcn_exp2f(s.y);
;     const f32x2 m = v * (q * e), r = v - m;
;     f32x2 o; o.x = v.x < 0.f ? m.x : r.x; o.y = v.y < 0.f ? m.y : r.y; return o;
; }
;     __device__ __forceinline__ void operator()(const f32x4 (&acc)[2][2][4][2], const Unit& u, int wr, int wc, int fr, int fq) const {
;     ...
;             for (int m = 0; m < 4; ++m) { bf16_t* rowp = O + (size_t)(u.pm >> 5) * bgap + (size_t)u.pm * sm + (size_t)u.pn * sn + (size_t)(wr * 64 + fr + ai * HALF + m * 16) * ldc + wc * 32 + 8 * fq; const float sc = rs[ai][m]; float s1 = 0.f, s2 = 0.f;
; #pragma unroll
;                 for (int bj = 0; bj < 2; ++bj) { f32x4 v0 = acc[ai][bj][m][0] * sc, v1 = acc[ai][bj][m][1] * sc;
;                     if (do_gelu) { f32x2 a = gelu_pk((f32x2){v0[0], v0[1]}), b = gelu_pk((f32x2){v0[2], v0[3]}), c = gelu_pk((f32x2){v1[0], v1[1]}), d = gelu_pk((f32x2){v1[2], v1[3]});
;                         v0 = (f32x4){a.x, a.y, b.x, b.y}; v1 = (f32x4){c.x, c.y, d.x, d.y}; }
;                     if (do_stat) { s1 += ((v0[0] + v0[1]) + (v0[2] + v0[3])) + ((v1[0] + v1[1]) + (v1[2] + v1[3]));
;                         s2 += ((v0[0] * v0[0] + v0[1] * v0[1]) + (v0[2] * v0[2] + v0[3] * v0[3])) + ((v1[0] * v1[0] + v1[1] * v1[1]) + (v1[2] * v1[2] + v1[3] * v1[3])); }
;                     u32x4 w; w.x = cvt_pk_bf16(v0[0], v0[1]); w.y = cvt_pk_bf16(v0[2], v0[3]); w.z = cvt_pk_bf16(v1[0], v1[1]); w.w = cvt_pk_bf16(v1[2], v1[3]);
;                     *(u32x4*)(rowp + bj * HALF) = w; }
.LBB0_330:
	v_lshl_add_u64 v[74:75], s[16:17], 0, v[142:143]
	v_lshl_add_u64 v[74:75], v[74:75], 0, s[86:87]
	v_lshl_add_u64 v[74:75], v[74:75], 0, v[192:193]
	v_cvt_pk_bf16_f32 v76, v76, v77
	v_cvt_pk_bf16_f32 v77, v78, v79
	v_mov_b32_e32 v165, v164
	v_cvt_pk_bf16_f32 v78, v82, v83
	v_cvt_pk_bf16_f32 v79, v80, v81
	global_store_dwordx4 v[74:75], v[76:79], off nt
	v_pk_mul_f32 v[68:69], v[68:69], v[164:165]
	s_and_b64 vcc, exec, s[42:43]
	v_mov_b32_e32 v76, v164
	v_mov_b32_e32 v77, v164
	v_pk_mul_f32 v[70:71], v[70:71], v[76:77]
	v_pk_mul_f32 v[66:67], v[66:67], v[76:77]
	v_pk_mul_f32 v[64:65], v[64:65], v[164:165]
	s_cbranch_vccnz .LBB0_332
	v_and_b32_e32 v77, 0x7fffffff, v69
	v_and_b32_e32 v76, 0x7fffffff, v68
	v_pk_fma_f32 v[76:77], v[76:77], s[28:29], 1.0 op_sel_hi:[1,0,0]
	s_mov_b32 s0, 0xbf3a00e3
	v_rcp_f32_e32 v78, v76
	v_rcp_f32_e32 v79, v77
	v_mov_b64_e32 v[76:77], s[0:1]
	v_pk_mul_f32 v[82:83], v[68:69], v[68:69]
	s_mov_b32 s0, 0xbf38aa3b
	v_pk_fma_f32 v[80:81], v[78:79], s[30:31], v[76:77] op_sel_hi:[1,0,0]
	v_pk_mul_f32 v[82:83], v[82:83], s[0:1] op_sel_hi:[1,0]
	v_pk_fma_f32 v[80:81], v[78:79], v[80:81], s[36:37] op_sel_hi:[1,1,0]
	v_exp_f32_e32 v82, v82
	v_exp_f32_e32 v83, v83
	v_pk_fma_f32 v[80:81], v[78:79], v[80:81], s[80:81] op_sel_hi:[1,1,0]
	v_cmp_gt_f32_e32 vcc, 0, v68
	v_pk_fma_f32 v[80:81], v[78:79], v[80:81], s[64:65] op_sel_hi:[1,1,0]
	s_nop 0
	v_pk_mul_f32 v[78:79], v[78:79], v[80:81]
	v_pk_mul_f32 v[80:81], v[70:71], v[70:71]
	v_pk_mul_f32 v[78:79], v[82:83], v[78:79]
	v_pk_mul_f32 v[80:81], v[80:81], s[0:1] op_sel_hi:[1,0]
	v_pk_mul_f32 v[82:83], v[68:69], v[78:79]
	v_pk_fma_f32 v[78:79], v[68:69], v[78:79], v[68:69] neg_lo:[1,0,0] neg_hi:[1,0,0]
	v_exp_f32_e32 v80, v80
	v_cndmask_b32_e32 v68, v78, v82, vcc
	v_cmp_gt_f32_e32 vcc, 0, v69
	v_and_b32_e32 v78, 0x7fffffff, v70
	v_exp_f32_e32 v81, v81
	v_cndmask_b32_e32 v69, v79, v83, vcc
	v_and_b32_e32 v79, 0x7fffffff, v71
	v_pk_fma_f32 v[78:79], v[78:79], s[28:29], 1.0 op_sel_hi:[1,0,0]
	v_cmp_gt_f32_e32 vcc, 0, v70
	v_rcp_f32_e32 v78, v78
	v_rcp_f32_e32 v79, v79
	s_nop 0
	v_pk_fma_f32 v[82:83], v[78:79], s[30:31], v[76:77] op_sel_hi:[1,0,0]
	s_nop 0
	v_pk_fma_f32 v[82:83], v[78:79], v[82:83], s[36:37] op_sel_hi:[1,1,0]
	s_nop 0
	v_pk_fma_f32 v[82:83], v[78:79], v[82:83], s[80:81] op_sel_hi:[1,1,0]
	s_nop 0
	v_pk_fma_f32 v[82:83], v[78:79], v[82:83], s[64:65] op_sel_hi:[1,1,0]
	s_nop 0
	v_pk_mul_f32 v[78:79], v[78:79], v[82:83]
	v_pk_mul_f32 v[82:83], v[64:65], v[64:65]
	v_pk_mul_f32 v[78:79], v[80:81], v[78:79]
	v_pk_mul_f32 v[82:83], v[82:83], s[0:1] op_sel_hi:[1,0]
	v_pk_mul_f32 v[80:81], v[70:71], v[78:79]
	v_pk_fma_f32 v[78:79], v[70:71], v[78:79], v[70:71] neg_lo:[1,0,0] neg_hi:[1,0,0]
	v_exp_f32_e32 v82, v82
	v_cndmask_b32_e32 v70, v78, v80, vcc
	v_cmp_gt_f32_e32 vcc, 0, v71
	v_and_b32_e32 v78, 0x7fffffff, v64
	v_exp_f32_e32 v83, v83
	v_cndmask_b32_e32 v71, v79, v81, vcc
	v_and_b32_e32 v79, 0x7fffffff, v65
	v_pk_fma_f32 v[78:79], v[78:79], s[28:29], 1.0 op_sel_hi:[1,0,0]
	v_cmp_gt_f32_e32 vcc, 0, v64
	v_rcp_f32_e32 v78, v78
	v_rcp_f32_e32 v79, v79
	s_nop 0
	v_pk_fma_f32 v[80:81], v[78:79], s[30:31], v[76:77] op_sel_hi:[1,0,0]
	s_nop 0
	v_pk_fma_f32 v[80:81], v[78:79], v[80:81], s[36:37] op_sel_hi:[1,1,0]
	s_nop 0
	v_pk_fma_f32 v[80:81], v[78:79], v[80:81], s[80:81] op_sel_hi:[1,1,0]
	s_nop 0
	v_pk_fma_f32 v[80:81], v[78:79], v[80:81], s[64:65] op_sel_hi:[1,1,0]
	s_nop 0
	v_pk_mul_f32 v[78:79], v[78:79], v[80:81]
	v_pk_mul_f32 v[80:81], v[66:67], v[66:67]
	v_pk_mul_f32 v[78:79], v[82:83], v[78:79]
	s_nop 0
	v_pk_mul_f32 v[82:83], v[64:65], v[78:79]
	v_pk_fma_f32 v[78:79], v[64:65], v[78:79], v[64:65] neg_lo:[1,0,0] neg_hi:[1,0,0]
	s_nop 0
	v_cndmask_b32_e32 v64, v78, v82, vcc
	v_cmp_gt_f32_e32 vcc, 0, v65
	v_and_b32_e32 v78, 0x7fffffff, v66
	s_nop 0
	v_cndmask_b32_e32 v65, v79, v83, vcc
	v_and_b32_e32 v79, 0x7fffffff, v67
	v_pk_fma_f32 v[78:79], v[78:79], s[28:29], 1.0 op_sel_hi:[1,0,0]
	v_cmp_gt_f32_e32 vcc, 0, v66
	v_rcp_f32_e32 v78, v78
	v_rcp_f32_e32 v79, v79
	s_nop 0
	v_pk_fma_f32 v[76:77], v[78:79], s[30:31], v[76:77] op_sel_hi:[1,0,0]
	s_nop 0
	v_pk_fma_f32 v[76:77], v[78:79], v[76:77], s[36:37] op_sel_hi:[1,1,0]
	s_nop 0
	v_pk_fma_f32 v[76:77], v[78:79], v[76:77], s[80:81] op_sel_hi:[1,1,0]
	s_nop 0
	v_pk_fma_f32 v[76:77], v[78:79], v[76:77], s[64:65] op_sel_hi:[1,1,0]
	s_nop 0
	v_pk_mul_f32 v[76:77], v[78:79], v[76:77]
	v_pk_mul_f32 v[78:79], v[80:81], s[0:1] op_sel_hi:[1,0]
	s_nop 0
	v_exp_f32_e32 v78, v78
	v_exp_f32_e32 v79, v79
	s_nop 0
	v_pk_mul_f32 v[76:77], v[78:79], v[76:77]
	s_nop 0
	v_pk_mul_f32 v[78:79], v[66:67], v[76:77]
	v_pk_fma_f32 v[76:77], v[66:67], v[76:77], v[66:67] neg_lo:[1,0,0] neg_hi:[1,0,0]
	s_nop 0
	v_cndmask_b32_e32 v66, v76, v78, vcc
	v_cmp_gt_f32_e32 vcc, 0, v67
	s_nop 1
	v_cndmask_b32_e32 v67, v77, v79, vcc

; __device__ __forceinline__ unsigned cvt_pk_bf16(float lo, float hi) { unsigned r; asm volatile("v_cvt_pk_bf16_f32 %0, %1, %2" : "=v"(r) : "v"(lo), "v"(hi)); return r; }
;     __device__ __forceinline__ void operator()(const f32x4 (&acc)[2][2][4][2], const Unit& u, int wr, int wc, int fr, int fq) const {
;     ...
;                     u32x4 w; w.x = cvt_pk_bf16(v0[0], v0[1]); w.y = cvt_pk_bf16(v0[2], v0[3]); w.z = cvt_pk_bf16(v1[0], v1[1]); w.w = cvt_pk_bf16(v1[2], v1[3]);
;                     *(u32x4*)(rowp + bj * HALF) = w; }
;                 if (do_stat) { s1 += __shfl_xor(s1, 16); s1 += __shfl_xor(s1, 32); s2 += __shfl_xor(s2, 16); s2 += __shfl_xor(s2, 32);
;                     if (fq == 0) *(f32x2*)(vstat + ((size_t)(row0 + ai * HALF + m * 16) * 8 + (u.pn - vstat_pn0) * 4 + wc) * 2) = (f32x2){s1, s2}; }
.LBB0_336:
	s_and_b64 vcc, exec, s[44:45]
	v_cvt_pk_bf16_f32 v68, v68, v69
	v_cvt_pk_bf16_f32 v69, v70, v71
	v_cvt_pk_bf16_f32 v70, v64, v65
	v_cvt_pk_bf16_f32 v71, v66, v67
	global_store_dwordx4 v[74:75], v[68:71], off offset:256 nt
	s_cbranch_vccnz .LBB0_340
	v_cmp_lt_i32_e32 vcc, v120, v119
	s_nop 1
	v_cndmask_b32_e32 v64, v252, v120, vcc
	v_lshlrev_b32_e32 v65, 2, v64
	ds_bpermute_b32 v64, v65, v76
	ds_bpermute_b32 v65, v65, v77
	v_cmp_lt_i32_e32 vcc, v118, v119
	s_waitcnt lgkmcnt(0)
	v_pk_add_f32 v[64:65], v[76:77], v[64:65]
	v_cndmask_b32_e32 v66, v252, v118, vcc
	v_lshlrev_b32_e32 v67, 2, v66
	ds_bpermute_b32 v66, v67, v64
	ds_bpermute_b32 v67, v67, v65
	s_and_saveexec_b64 s[0:1], s[38:39]
	s_cbranch_execz .LBB0_339
	s_lshl_b32 s4, s60, 2
	s_waitcnt lgkmcnt(0)
	v_pk_add_f32 v[64:65], v[64:65], v[66:67]
	v_or_b32_e32 v66, 48, v112
	s_add_i32 s4, s4, -16
	v_ashrrev_i32_e32 v67, 31, v66
	v_mov_b32_e32 v68, s4
	v_mov_b32_e32 v69, v193
	v_lshl_add_u64 v[66:67], v[66:67], 3, v[68:69]
	v_or_b32_e32 v66, s83, v66
	v_lshl_add_u64 v[66:67], v[66:67], 3, s[20:21]
	global_store_dwordx2 v[66:67], v[64:65], off

; __device__ __forceinline__ unsigned cvt_pk_bf16(float lo, float hi) { unsigned r; asm volatile("v_cvt_pk_bf16_f32 %0, %1, %2" : "=v"(r) : "v"(lo), "v"(hi)); return r; }
; __device__ __forceinline__ f32x2 gelu_pk(f32x2 v) {
;     const f32x2 av = __builtin_elementwise_abs(v), d = av * 0.2316418882f + 1.0f;
;     f32x2 t; t.x = __builtin_amdgcn_rcpf(d.x); t.y = __builtin_amdgcn_rcpf(d.y);
;     f32x2 q = t * 0.5307027145f + (-0.7265760135f); q = q * t + 0.7107068705f; q = q * t + (-0.142248368f); q = q * t + 0.127414796f; q = q * t;
;     const f32x2 s = (v * v) * (-0.72134752044f);
;     f32x2 e; e.x = __builtin_amdgcn_exp2f(s.x); e.y = __builtin_amdgcn_exp2f(s.y);
;     const f32x2 m = v * (q * e), r = v - m;
;     f32x2 o; o.x = v.x < 0.f ? m.x : r.x; o.y = v.y < 0.f ? m.y : r.y; return o;
; }
;     __device__ __forceinline__ void operator()(const f32x4 (&acc)[2][2][4][2], const Unit& u, int wr, int wc, int fr, int fq) const {
;     ...
;             for (int m = 0; m < 4; ++m) { bf16_t* rowp = O + (size_t)(u.pm >> 5) * bgap + (size_t)u.pm * sm + (size_t)u.pn * sn + (size_t)(wr * 64 + fr + ai * HALF + m * 16) * ldc + wc * 32 + 8 * fq; const float sc = rs[ai][m]; float s1 = 0.f, s2 = 0.f;
; #pragma unroll
;                 for (int bj = 0; bj < 2; ++bj) { f32x4 v0 = acc[ai][bj][m][0] * sc, v1 = acc[ai][bj][m][1] * sc;
;                     if (do_gelu) { f32x2 a = gelu_pk((f32x2){v0[0], v0[1]}), b = gelu_pk((f32x2){v0[2], v0[3]}), c = gelu_pk((f32x2){v1[0], v1[1]}), d = gelu_pk((f32x2){v1[2], v1[3]});
;                         v0 = (f32x4){a.x, a.y, b.x, b.y}; v1 = (f32x4){c.x, c.y, d.x, d.y}; }
;                     if (do_stat) { s1 += ((v0[0] + v0[1]) + (v0[2] + v0[3])) + ((v1[0] + v1[1]) + (v1[2] + v1[3]));
;                         s2 += ((v0[0] * v0[0] + v0[1] * v0[1]) + (v0[2] * v0[2] + v0[3] * v0[3])) + ((v1[0] * v1[0] + v1[1] * v1[1]) + (v1[2] * v1[2] + v1[3] * v1[3])); }
;                     u32x4 w; w.x = cvt_pk_bf16(v0[0], v0[1]); w.y = cvt_pk_bf16(v0[2], v0[3]); w.z = cvt_pk_bf16(v1[0], v1[1]); w.w = cvt_pk_bf16(v1[2], v1[3]);
;                     *(u32x4*)(rowp + bj * HALF) = w; }
.LBB0_346:
	v_lshl_add_u64 v[58:59], s[16:17], 0, v[144:145]
	v_lshl_add_u64 v[58:59], v[58:59], 0, s[86:87]
	v_lshl_add_u64 v[58:59], v[58:59], 0, v[192:193]
	v_cvt_pk_bf16_f32 v60, v60, v61
	v_cvt_pk_bf16_f32 v61, v62, v63
	v_mov_b32_e32 v163, v162
	v_cvt_pk_bf16_f32 v62, v66, v67
	v_cvt_pk_bf16_f32 v63, v64, v65
	global_store_dwordx4 v[58:59], v[60:63], off nt
	v_pk_mul_f32 v[52:53], v[52:53], v[162:163]
	s_and_b64 vcc, exec, s[42:43]
	v_mov_b32_e32 v60, v162
	v_mov_b32_e32 v61, v162
	v_pk_mul_f32 v[54:55], v[54:55], v[60:61]
	v_pk_mul_f32 v[50:51], v[50:51], v[60:61]
	v_pk_mul_f32 v[48:49], v[48:49], v[162:163]
	s_cbranch_vccnz .LBB0_348
	v_and_b32_e32 v61, 0x7fffffff, v53
	v_and_b32_e32 v60, 0x7fffffff, v52
	v_pk_fma_f32 v[60:61], v[60:61], s[28:29], 1.0 op_sel_hi:[1,0,0]
	s_mov_b32 s0, 0xbf3a00e3
	v_rcp_f32_e32 v62, v60
	v_rcp_f32_e32 v63, v61
	v_mov_b64_e32 v[60:61], s[0:1]
	v_pk_mul_f32 v[66:67], v[52:53], v[52:53]
	s_mov_b32 s0, 0xbf38aa3b
	v_pk_fma_f32 v[64:65], v[62:63], s[30:31], v[60:61] op_sel_hi:[1,0,0]
	v_pk_mul_f32 v[66:67], v[66:67], s[0:1] op_sel_hi:[1,0]
	v_pk_fma_f32 v[64:65], v[62:63], v[64:65], s[36:37] op_sel_hi:[1,1,0]
	v_exp_f32_e32 v66, v66
	v_exp_f32_e32 v67, v67
	v_pk_fma_f32 v[64:65], v[62:63], v[64:65], s[80:81] op_sel_hi:[1,1,0]
	v_cmp_gt_f32_e32 vcc, 0, v52
	v_pk_fma_f32 v[64:65], v[62:63], v[64:65], s[64:65] op_sel_hi:[1,1,0]
	s_nop 0
	v_pk_mul_f32 v[62:63], v[62:63], v[64:65]
	v_pk_mul_f32 v[64:65], v[54:55], v[54:55]
	v_pk_mul_f32 v[62:63], v[66:67], v[62:63]
	v_pk_mul_f32 v[64:65], v[64:65], s[0:1] op_sel_hi:[1,0]
	v_pk_mul_f32 v[66:67], v[52:53], v[62:63]
	v_pk_fma_f32 v[62:63], v[52:53], v[62:63], v[52:53] neg_lo:[1,0,0] neg_hi:[1,0,0]
	v_exp_f32_e32 v64, v64
	v_cndmask_b32_e32 v52, v62, v66, vcc
	v_cmp_gt_f32_e32 vcc, 0, v53
	v_and_b32_e32 v62, 0x7fffffff, v54
	v_exp_f32_e32 v65, v65
	v_cndmask_b32_e32 v53, v63, v67, vcc
	v_and_b32_e32 v63, 0x7fffffff, v55
	v_pk_fma_f32 v[62:63], v[62:63], s[28:29], 1.0 op_sel_hi:[1,0,0]
	v_cmp_gt_f32_e32 vcc, 0, v54
	v_rcp_f32_e32 v62, v62
	v_rcp_f32_e32 v63, v63
	s_nop 0
	v_pk_fma_f32 v[66:67], v[62:63], s[30:31], v[60:61] op_sel_hi:[1,0,0]
	s_nop 0
	v_pk_fma_f32 v[66:67], v[62:63], v[66:67], s[36:37] op_sel_hi:[1,1,0]
	s_nop 0
	v_pk_fma_f32 v[66:67], v[62:63], v[66:67], s[80:81] op_sel_hi:[1,1,0]
	s_nop 0
	v_pk_fma_f32 v[66:67], v[62:63], v[66:67], s[64:65] op_sel_hi:[1,1,0]
	s_nop 0
	v_pk_mul_f32 v[62:63], v[62:63], v[66:67]
	v_pk_mul_f32 v[66:67], v[48:49], v[48:49]
	v_pk_mul_f32 v[62:63], v[64:65], v[62:63]
	v_pk_mul_f32 v[66:67], v[66:67], s[0:1] op_sel_hi:[1,0]
	v_pk_mul_f32 v[64:65], v[54:55], v[62:63]
	v_pk_fma_f32 v[62:63], v[54:55], v[62:63], v[54:55] neg_lo:[1,0,0] neg_hi:[1,0,0]
	v_exp_f32_e32 v66, v66
	v_cndmask_b32_e32 v54, v62, v64, vcc
	v_cmp_gt_f32_e32 vcc, 0, v55
	v_and_b32_e32 v62, 0x7fffffff, v48
	v_exp_f32_e32 v67, v67
	v_cndmask_b32_e32 v55, v63, v65, vcc
	v_and_b32_e32 v63, 0x7fffffff, v49
	v_pk_fma_f32 v[62:63], v[62:63], s[28:29], 1.0 op_sel_hi:[1,0,0]
	v_cmp_gt_f32_e32 vcc, 0, v48
	v_rcp_f32_e32 v62, v62
	v_rcp_f32_e32 v63, v63
	s_nop 0
	v_pk_fma_f32 v[64:65], v[62:63], s[30:31], v[60:61] op_sel_hi:[1,0,0]
	s_nop 0
	v_pk_fma_f32 v[64:65], v[62:63], v[64:65], s[36:37] op_sel_hi:[1,1,0]
	s_nop 0
	v_pk_fma_f32 v[64:65], v[62:63], v[64:65], s[80:81] op_sel_hi:[1,1,0]
	s_nop 0
	v_pk_fma_f32 v[64:65], v[62:63], v[64:65], s[64:65] op_sel_hi:[1,1,0]
	s_nop 0
	v_pk_mul_f32 v[62:63], v[62:63], v[64:65]
	v_pk_mul_f32 v[64:65], v[50:51], v[50:51]
	v_pk_mul_f32 v[62:63], v[66:67], v[62:63]
	s_nop 0
	v_pk_mul_f32 v[66:67], v[48:49], v[62:63]
	v_pk_fma_f32 v[62:63], v[48:49], v[62:63], v[48:49] neg_lo:[1,0,0] neg_hi:[1,0,0]
	s_nop 0
	v_cndmask_b32_e32 v48, v62, v66, vcc
	v_cmp_gt_f32_e32 vcc, 0, v49
	v_and_b32_e32 v62, 0x7fffffff, v50
	s_nop 0
	v_cndmask_b32_e32 v49, v63, v67, vcc
	v_and_b32_e32 v63, 0x7fffffff, v51
	v_pk_fma_f32 v[62:63], v[62:63], s[28:29], 1.0 op_sel_hi:[1,0,0]
	v_cmp_gt_f32_e32 vcc, 0, v50
	v_rcp_f32_e32 v62, v62
	v_rcp_f32_e32 v63, v63
	s_nop 0
	v_pk_fma_f32 v[60:61], v[62:63], s[30:31], v[60:61] op_sel_hi:[1,0,0]
	s_nop 0
	v_pk_fma_f32 v[60:61], v[62:63], v[60:61], s[36:37] op_sel_hi:[1,1,0]
	s_nop 0
	v_pk_fma_f32 v[60:61], v[62:63], v[60:61], s[80:81] op_sel_hi:[1,1,0]
	s_nop 0
	v_pk_fma_f32 v[60:61], v[62:63], v[60:61], s[64:65] op_sel_hi:[1,1,0]
	s_nop 0
	v_pk_mul_f32 v[60:61], v[62:63], v[60:61]
	v_pk_mul_f32 v[62:63], v[64:65], s[0:1] op_sel_hi:[1,0]
	s_nop 0
	v_exp_f32_e32 v62, v62
	v_exp_f32_e32 v63, v63
	s_nop 0
	v_pk_mul_f32 v[60:61], v[62:63], v[60:61]
	s_nop 0
	v_pk_mul_f32 v[62:63], v[50:51], v[60:61]
	v_pk_fma_f32 v[60:61], v[50:51], v[60:61], v[50:51] neg_lo:[1,0,0] neg_hi:[1,0,0]
	s_nop 0
	v_cndmask_b32_e32 v50, v60, v62, vcc
	v_cmp_gt_f32_e32 vcc, 0, v51
	s_nop 1
	v_cndmask_b32_e32 v51, v61, v63, vcc

; __device__ __forceinline__ unsigned cvt_pk_bf16(float lo, float hi) { unsigned r; asm volatile("v_cvt_pk_bf16_f32 %0, %1, %2" : "=v"(r) : "v"(lo), "v"(hi)); return r; }
;     __device__ __forceinline__ void operator()(const f32x4 (&acc)[2][2][4][2], const Unit& u, int wr, int wc, int fr, int fq) const {
;     ...
;                     u32x4 w; w.x = cvt_pk_bf16(v0[0], v0[1]); w.y = cvt_pk_bf16(v0[2], v0[3]); w.z = cvt_pk_bf16(v1[0], v1[1]); w.w = cvt_pk_bf16(v1[2], v1[3]);
;                     *(u32x4*)(rowp + bj * HALF) = w; }
;                 if (do_stat) { s1 += __shfl_xor(s1, 16); s1 += __shfl_xor(s1, 32); s2 += __shfl_xor(s2, 16); s2 += __shfl_xor(s2, 32);
;                     if (fq == 0) *(f32x2*)(vstat + ((size_t)(row0 + ai * HALF + m * 16) * 8 + (u.pn - vstat_pn0) * 4 + wc) * 2) = (f32x2){s1, s2}; }
.LBB0_352:
	s_and_b64 vcc, exec, s[44:45]
	v_cvt_pk_bf16_f32 v52, v52, v53
	v_cvt_pk_bf16_f32 v53, v54, v55
	v_cvt_pk_bf16_f32 v54, v48, v49
	v_cvt_pk_bf16_f32 v55, v50, v51
	global_store_dwordx4 v[58:59], v[52:55], off offset:256 nt
	s_cbranch_vccnz .LBB0_356
	v_cmp_lt_i32_e32 vcc, v120, v119
	s_nop 1
	v_cndmask_b32_e32 v48, v252, v120, vcc
	v_lshlrev_b32_e32 v49, 2, v48
	ds_bpermute_b32 v48, v49, v60
	ds_bpermute_b32 v49, v49, v61
	v_cmp_lt_i32_e32 vcc, v118, v119
	s_waitcnt lgkmcnt(0)
	v_pk_add_f32 v[48:49], v[60:61], v[48:49]
	v_cndmask_b32_e32 v50, v252, v118, vcc
	v_lshlrev_b32_e32 v51, 2, v50
	ds_bpermute_b32 v50, v51, v48
	ds_bpermute_b32 v51, v51, v49
	s_and_saveexec_b64 s[0:1], s[38:39]
	s_cbranch_execz .LBB0_355
	s_lshl_b32 s4, s60, 2
	s_add_i32 s4, s4, -16
	s_waitcnt lgkmcnt(0)
	v_pk_add_f32 v[48:49], v[48:49], v[50:51]
	v_ashrrev_i32_e32 v113, 31, v112
	v_mov_b32_e32 v50, s4
	v_mov_b32_e32 v51, v193
	v_lshl_add_u64 v[50:51], v[112:113], 3, v[50:51]
	v_or_b32_e32 v50, s83, v50
	v_lshl_add_u64 v[50:51], v[50:51], 3, s[20:21]
	v_add_co_u32_e32 v50, vcc, 0x2000, v50
	s_nop 1
	v_addc_co_u32_e32 v51, vcc, 0, v51, vcc
	global_store_dwordx2 v[50:51], v[48:49], off

; __device__ __forceinline__ unsigned cvt_pk_bf16(float lo, float hi) { unsigned r; asm volatile("v_cvt_pk_bf16_f32 %0, %1, %2" : "=v"(r) : "v"(lo), "v"(hi)); return r; }
; __device__ __forceinline__ f32x2 gelu_pk(f32x2 v) {
;     const f32x2 av = __builtin_elementwise_abs(v), d = av * 0.2316418882f + 1.0f;
;     f32x2 t; t.x = __builtin_amdgcn_rcpf(d.x); t.y = __builtin_amdgcn_rcpf(d.y);
;     f32x2 q = t * 0.5307027145f + (-0.7265760135f); q = q * t + 0.7107068705f; q = q * t + (-0.142248368f); q = q * t + 0.127414796f; q = q * t;
;     const f32x2 s = (v * v) * (-0.72134752044f);
;     f32x2 e; e.x = __builtin_amdgcn_exp2f(s.x); e.y = __builtin_amdgcn_exp2f(s.y);
;     const f32x2 m = v * (q * e), r = v - m;
;     f32x2 o; o.x = v.x < 0.f ? m.x : r.x; o.y = v.y < 0.f ? m.y : r.y; return o;
;     __device__ __forceinline__ void operator()(const f32x4 (&acc)[2][2][4][2], const Unit& u, int wr, int wc, int fr, int fq) const {
;     ...
;             for (int m = 0; m < 4; ++m) { bf16_t* rowp = O + (size_t)(u.pm >> 5) * bgap + (size_t)u.pm * sm + (size_t)u.pn * sn + (size_t)(wr * 64 + fr + ai * HALF + m * 16) * ldc + wc * 32 + 8 * fq; const float sc = rs[ai][m]; float s1 = 0.f, s2 = 0.f;
; #pragma unroll
;                 for (int bj = 0; bj < 2; ++bj) { f32x4 v0 = acc[ai][bj][m][0] * sc, v1 = acc[ai][bj][m][1] * sc;
;                     if (do_gelu) { f32x2 a = gelu_pk((f32x2){v0[0], v0[1]}), b = gelu_pk((f32x2){v0[2], v0[3]}), c = gelu_pk((f32x2){v1[0], v1[1]}), d = gelu_pk((f32x2){v1[2], v1[3]});
;                         v0 = (f32x4){a.x, a.y, b.x, b.y}; v1 = (f32x4){c.x, c.y, d.x, d.y}; }
;                     if (do_stat) { s1 += ((v0[0] + v0[1]) + (v0[2] + v0[3])) + ((v1[0] + v1[1]) + (v1[2] + v1[3]));
;                         s2 += ((v0[0] * v0[0] + v0[1] * v0[1]) + (v0[2] * v0[2] + v0[3] * v0[3])) + ((v1[0] * v1[0] + v1[1] * v1[1]) + (v1[2] * v1[2] + v1[3] * v1[3])); }
;                     u32x4 w; w.x = cvt_pk_bf16(v0[0], v0[1]); w.y = cvt_pk_bf16(v0[2], v0[3]); w.z = cvt_pk_bf16(v1[0], v1[1]); w.w = cvt_pk_bf16(v1[2], v1[3]);
;                     *(u32x4*)(rowp + bj * HALF) = w; }
.LBB0_362:
	v_lshl_add_u64 v[42:43], s[16:17], 0, v[146:147]
	v_lshl_add_u64 v[42:43], v[42:43], 0, s[86:87]
	v_lshl_add_u64 v[42:43], v[42:43], 0, v[192:193]
	v_cvt_pk_bf16_f32 v44, v44, v45
	v_cvt_pk_bf16_f32 v45, v46, v47
	v_mov_b32_e32 v161, v160
	v_cvt_pk_bf16_f32 v46, v50, v51
	v_cvt_pk_bf16_f32 v47, v48, v49
	global_store_dwordx4 v[42:43], v[44:47], off nt
	v_pk_mul_f32 v[36:37], v[36:37], v[160:161]
	s_and_b64 vcc, exec, s[42:43]
	v_mov_b32_e32 v44, v160
	v_mov_b32_e32 v45, v160
	v_pk_mul_f32 v[38:39], v[38:39], v[44:45]
	v_pk_mul_f32 v[34:35], v[34:35], v[44:45]
	v_pk_mul_f32 v[32:33], v[32:33], v[160:161]
	s_cbranch_vccnz .LBB0_364
	v_and_b32_e32 v45, 0x7fffffff, v37
	v_and_b32_e32 v44, 0x7fffffff, v36
	v_pk_fma_f32 v[44:45], v[44:45], s[28:29], 1.0 op_sel_hi:[1,0,0]
	s_mov_b32 s0, 0xbf3a00e3
	v_rcp_f32_e32 v46, v44
	v_rcp_f32_e32 v47, v45
	v_mov_b64_e32 v[44:45], s[0:1]
	v_pk_mul_f32 v[50:51], v[36:37], v[36:37]
	s_mov_b32 s0, 0xbf38aa3b
	v_pk_fma_f32 v[48:49], v[46:47], s[30:31], v[44:45] op_sel_hi:[1,0,0]
	v_pk_mul_f32 v[50:51], v[50:51], s[0:1] op_sel_hi:[1,0]
	v_pk_fma_f32 v[48:49], v[46:47], v[48:49], s[36:37] op_sel_hi:[1,1,0]
	v_exp_f32_e32 v50, v50
	v_exp_f32_e32 v51, v51
	v_pk_fma_f32 v[48:49], v[46:47], v[48:49], s[80:81] op_sel_hi:[1,1,0]
	v_cmp_gt_f32_e32 vcc, 0, v36
	v_pk_fma_f32 v[48:49], v[46:47], v[48:49], s[64:65] op_sel_hi:[1,1,0]
	s_nop 0
	v_pk_mul_f32 v[46:47], v[46:47], v[48:49]
	v_pk_mul_f32 v[48:49], v[38:39], v[38:39]
	v_pk_mul_f32 v[46:47], v[50:51], v[46:47]
	v_pk_mul_f32 v[48:49], v[48:49], s[0:1] op_sel_hi:[1,0]
	v_pk_mul_f32 v[50:51], v[36:37], v[46:47]
	v_pk_fma_f32 v[46:47], v[36:37], v[46:47], v[36:37] neg_lo:[1,0,0] neg_hi:[1,0,0]
	v_exp_f32_e32 v48, v48
	v_cndmask_b32_e32 v36, v46, v50, vcc
	v_cmp_gt_f32_e32 vcc, 0, v37
	v_and_b32_e32 v46, 0x7fffffff, v38
	v_exp_f32_e32 v49, v49
	v_cndmask_b32_e32 v37, v47, v51, vcc
	v_and_b32_e32 v47, 0x7fffffff, v39
	v_pk_fma_f32 v[46:47], v[46:47], s[28:29], 1.0 op_sel_hi:[1,0,0]
	v_cmp_gt_f32_e32 vcc, 0, v38
	v_rcp_f32_e32 v46, v46
	v_rcp_f32_e32 v47, v47
	s_nop 0
	v_pk_fma_f32 v[50:51], v[46:47], s[30:31], v[44:45] op_sel_hi:[1,0,0]
	s_nop 0
	v_pk_fma_f32 v[50:51], v[46:47], v[50:51], s[36:37] op_sel_hi:[1,1,0]
	s_nop 0
	v_pk_fma_f32 v[50:51], v[46:47], v[50:51], s[80:81] op_sel_hi:[1,1,0]
	s_nop 0
	v_pk_fma_f32 v[50:51], v[46:47], v[50:51], s[64:65] op_sel_hi:[1,1,0]
	s_nop 0
	v_pk_mul_f32 v[46:47], v[46:47], v[50:51]
	v_pk_mul_f32 v[50:51], v[32:33], v[32:33]
	v_pk_mul_f32 v[46:47], v[48:49], v[46:47]
	v_pk_mul_f32 v[50:51], v[50:51], s[0:1] op_sel_hi:[1,0]
	v_pk_mul_f32 v[48:49], v[38:39], v[46:47]
	v_pk_fma_f32 v[46:47], v[38:39], v[46:47], v[38:39] neg_lo:[1,0,0] neg_hi:[1,0,0]
	v_exp_f32_e32 v50, v50
	v_cndmask_b32_e32 v38, v46, v48, vcc
	v_cmp_gt_f32_e32 vcc, 0, v39
	v_and_b32_e32 v46, 0x7fffffff, v32
	v_exp_f32_e32 v51, v51
	v_cndmask_b32_e32 v39, v47, v49, vcc
	v_and_b32_e32 v47, 0x7fffffff, v33
	v_pk_fma_f32 v[46:47], v[46:47], s[28:29], 1.0 op_sel_hi:[1,0,0]
	v_cmp_gt_f32_e32 vcc, 0, v32
	v_rcp_f32_e32 v46, v46
	v_rcp_f32_e32 v47, v47
	s_nop 0
	v_pk_fma_f32 v[48:49], v[46:47], s[30:31], v[44:45] op_sel_hi:[1,0,0]
	s_nop 0
	v_pk_fma_f32 v[48:49], v[46:47], v[48:49], s[36:37] op_sel_hi:[1,1,0]
	s_nop 0
	v_pk_fma_f32 v[48:49], v[46:47], v[48:49], s[80:81] op_sel_hi:[1,1,0]
	s_nop 0
	v_pk_fma_f32 v[48:49], v[46:47], v[48:49], s[64:65] op_sel_hi:[1,1,0]
	s_nop 0
	v_pk_mul_f32 v[46:47], v[46:47], v[48:49]
	v_pk_mul_f32 v[48:49], v[34:35], v[34:35]
	v_pk_mul_f32 v[46:47], v[50:51], v[46:47]
	s_nop 0
	v_pk_mul_f32 v[50:51], v[32:33], v[46:47]
	v_pk_fma_f32 v[46:47], v[32:33], v[46:47], v[32:33] neg_lo:[1,0,0] neg_hi:[1,0,0]
	s_nop 0
	v_cndmask_b32_e32 v32, v46, v50, vcc
	v_cmp_gt_f32_e32 vcc, 0, v33
	v_and_b32_e32 v46, 0x7fffffff, v34
	s_nop 0
	v_cndmask_b32_e32 v33, v47, v51, vcc
	v_and_b32_e32 v47, 0x7fffffff, v35
	v_pk_fma_f32 v[46:47], v[46:47], s[28:29], 1.0 op_sel_hi:[1,0,0]
	v_cmp_gt_f32_e32 vcc, 0, v34
	v_rcp_f32_e32 v46, v46
	v_rcp_f32_e32 v47, v47
	s_nop 0
	v_pk_fma_f32 v[44:45], v[46:47], s[30:31], v[44:45] op_sel_hi:[1,0,0]
	s_nop 0
	v_pk_fma_f32 v[44:45], v[46:47], v[44:45], s[36:37] op_sel_hi:[1,1,0]
	s_nop 0
	v_pk_fma_f32 v[44:45], v[46:47], v[44:45], s[80:81] op_sel_hi:[1,1,0]
	s_nop 0
	v_pk_fma_f32 v[44:45], v[46:47], v[44:45], s[64:65] op_sel_hi:[1,1,0]
	s_nop 0
	v_pk_mul_f32 v[44:45], v[46:47], v[44:45]
	v_pk_mul_f32 v[46:47], v[48:49], s[0:1] op_sel_hi:[1,0]
	s_nop 0
	v_exp_f32_e32 v46, v46
	v_exp_f32_e32 v47, v47
	s_nop 0
	v_pk_mul_f32 v[44:45], v[46:47], v[44:45]
	s_nop 0
	v_pk_mul_f32 v[46:47], v[34:35], v[44:45]
	v_pk_fma_f32 v[44:45], v[34:35], v[44:45], v[34:35] neg_lo:[1,0,0] neg_hi:[1,0,0]
	s_nop 0
	v_cndmask_b32_e32 v34, v44, v46, vcc
	v_cmp_gt_f32_e32 vcc, 0, v35
	s_nop 1
	v_cndmask_b32_e32 v35, v45, v47, vcc

; __device__ __forceinline__ unsigned cvt_pk_bf16(float lo, float hi) { unsigned r; asm volatile("v_cvt_pk_bf16_f32 %0, %1, %2" : "=v"(r) : "v"(lo), "v"(hi)); return r; }
;     __device__ __forceinline__ void operator()(const f32x4 (&acc)[2][2][4][2], const Unit& u, int wr, int wc, int fr, int fq) const {
;     ...
;                     u32x4 w; w.x = cvt_pk_bf16(v0[0], v0[1]); w.y = cvt_pk_bf16(v0[2], v0[3]); w.z = cvt_pk_bf16(v1[0], v1[1]); w.w = cvt_pk_bf16(v1[2], v1[3]);
;                     *(u32x4*)(rowp + bj * HALF) = w; }
;                 if (do_stat) { s1 += __shfl_xor(s1, 16); s1 += __shfl_xor(s1, 32); s2 += __shfl_xor(s2, 16); s2 += __shfl_xor(s2, 32);
;                     if (fq == 0) *(f32x2*)(vstat + ((size_t)(row0 + ai * HALF + m * 16) * 8 + (u.pn - vstat_pn0) * 4 + wc) * 2) = (f32x2){s1, s2}; }
.LBB0_368:
	s_and_b64 vcc, exec, s[44:45]
	v_cvt_pk_bf16_f32 v36, v36, v37
	v_cvt_pk_bf16_f32 v37, v38, v39
	v_cvt_pk_bf16_f32 v38, v32, v33
	v_cvt_pk_bf16_f32 v39, v34, v35
	global_store_dwordx4 v[42:43], v[36:39], off offset:256 nt
	s_cbranch_vccnz .LBB0_372
	v_cmp_lt_i32_e32 vcc, v120, v119
	s_nop 1
	v_cndmask_b32_e32 v32, v252, v120, vcc
	v_lshlrev_b32_e32 v33, 2, v32
	ds_bpermute_b32 v32, v33, v44
	ds_bpermute_b32 v33, v33, v45
	v_cmp_lt_i32_e32 vcc, v118, v119
	s_waitcnt lgkmcnt(0)
	v_pk_add_f32 v[32:33], v[44:45], v[32:33]
	v_cndmask_b32_e32 v34, v252, v118, vcc
	v_lshlrev_b32_e32 v35, 2, v34
	ds_bpermute_b32 v34, v35, v32
	ds_bpermute_b32 v35, v35, v33
	s_and_saveexec_b64 s[0:1], s[38:39]
	s_cbranch_execz .LBB0_371
	s_lshl_b32 s4, s60, 2
	s_add_i32 s4, s4, -16
	s_waitcnt lgkmcnt(0)
	v_pk_add_f32 v[32:33], v[32:33], v[34:35]
	v_ashrrev_i32_e32 v113, 31, v112
	v_mov_b32_e32 v34, s4
	v_mov_b32_e32 v35, v193
	v_lshl_add_u64 v[34:35], v[112:113], 3, v[34:35]
	v_or_b32_e32 v34, s83, v34
	v_lshl_add_u64 v[34:35], v[34:35], 3, s[20:21]
	v_add_co_u32_e32 v34, vcc, 0x2000, v34
	s_nop 1
	v_addc_co_u32_e32 v35, vcc, 0, v35, vcc
	global_store_dwordx2 v[34:35], v[32:33], off offset:1024

; __device__ __forceinline__ unsigned cvt_pk_bf16(float lo, float hi) { unsigned r; asm volatile("v_cvt_pk_bf16_f32 %0, %1, %2" : "=v"(r) : "v"(lo), "v"(hi)); return r; }
; __device__ __forceinline__ f32x2 gelu_pk(f32x2 v) {
;     const f32x2 av = __builtin_elementwise_abs(v), d = av * 0.2316418882f + 1.0f;
;     f32x2 t; t.x = __builtin_amdgcn_rcpf(d.x); t.y = __builtin_amdgcn_rcpf(d.y);
;     f32x2 q = t * 0.5307027145f + (-0.7265760135f); q = q * t + 0.7107068705f; q = q * t + (-0.142248368f); q = q * t + 0.127414796f; q = q * t;
;     const f32x2 s = (v * v) * (-0.72134752044f);
;     f32x2 e; e.x = __builtin_amdgcn_exp2f(s.x); e.y = __builtin_amdgcn_exp2f(s.y);
;     const f32x2 m = v * (q * e), r = v - m;
;     f32x2 o; o.x = v.x < 0.f ? m.x : r.x; o.y = v.y < 0.f ? m.y : r.y; return o;
;     __device__ __forceinline__ void operator()(const f32x4 (&acc)[2][2][4][2], const Unit& u, int wr, int wc, int fr, int fq) const {
;     ...
;                 for (int bj = 0; bj < 2; ++bj) { f32x4 v0 = acc[ai][bj][m][0] * sc, v1 = acc[ai][bj][m][1] * sc;
;                     if (do_gelu) { f32x2 a = gelu_pk((f32x2){v0[0], v0[1]}), b = gelu_pk((f32x2){v0[2], v0[3]}), c = gelu_pk((f32x2){v1[0], v1[1]}), d = gelu_pk((f32x2){v1[2], v1[3]});
;                         v0 = (f32x4){a.x, a.y, b.x, b.y}; v1 = (f32x4){c.x, c.y, d.x, d.y}; }
;                     if (do_stat) { s1 += ((v0[0] + v0[1]) + (v0[2] + v0[3])) + ((v1[0] + v1[1]) + (v1[2] + v1[3]));
;                         s2 += ((v0[0] * v0[0] + v0[1] * v0[1]) + (v0[2] * v0[2] + v0[3] * v0[3])) + ((v1[0] * v1[0] + v1[1] * v1[1]) + (v1[2] * v1[2] + v1[3] * v1[3])); }
;                     u32x4 w; w.x = cvt_pk_bf16(v0[0], v0[1]); w.y = cvt_pk_bf16(v0[2], v0[3]); w.z = cvt_pk_bf16(v1[0], v1[1]); w.w = cvt_pk_bf16(v1[2], v1[3]);
;                     *(u32x4*)(rowp + bj * HALF) = w; }
.LBB0_378:
	v_lshl_add_u64 v[26:27], s[16:17], 0, v[148:149]
	v_lshl_add_u64 v[26:27], v[26:27], 0, s[86:87]
	v_lshl_add_u64 v[26:27], v[26:27], 0, v[192:193]
	v_cvt_pk_bf16_f32 v28, v28, v29
	v_cvt_pk_bf16_f32 v29, v30, v31
	v_mov_b32_e32 v159, v158
	v_cvt_pk_bf16_f32 v30, v34, v35
	v_cvt_pk_bf16_f32 v31, v32, v33
	global_store_dwordx4 v[26:27], v[28:31], off nt
	v_pk_mul_f32 v[20:21], v[20:21], v[158:159]
	s_and_b64 vcc, exec, s[42:43]
	v_mov_b32_e32 v28, v158
	v_mov_b32_e32 v29, v158
	v_pk_mul_f32 v[22:23], v[22:23], v[28:29]
	v_pk_mul_f32 v[18:19], v[18:19], v[28:29]
	v_pk_mul_f32 v[16:17], v[16:17], v[158:159]
	s_cbranch_vccnz .LBB0_380
	v_and_b32_e32 v29, 0x7fffffff, v21
	v_and_b32_e32 v28, 0x7fffffff, v20
	v_pk_fma_f32 v[28:29], v[28:29], s[28:29], 1.0 op_sel_hi:[1,0,0]
	s_mov_b32 s0, 0xbf3a00e3
	v_rcp_f32_e32 v30, v28
	v_rcp_f32_e32 v31, v29
	v_mov_b64_e32 v[28:29], s[0:1]
	v_pk_mul_f32 v[34:35], v[20:21], v[20:21]
	s_mov_b32 s0, 0xbf38aa3b
	v_pk_fma_f32 v[32:33], v[30:31], s[30:31], v[28:29] op_sel_hi:[1,0,0]
	v_pk_mul_f32 v[34:35], v[34:35], s[0:1] op_sel_hi:[1,0]
	v_pk_fma_f32 v[32:33], v[30:31], v[32:33], s[36:37] op_sel_hi:[1,1,0]
	v_exp_f32_e32 v34, v34
	v_exp_f32_e32 v35, v35
	v_pk_fma_f32 v[32:33], v[30:31], v[32:33], s[80:81] op_sel_hi:[1,1,0]
	v_cmp_gt_f32_e32 vcc, 0, v20
	v_pk_fma_f32 v[32:33], v[30:31], v[32:33], s[64:65] op_sel_hi:[1,1,0]
	s_nop 0
	v_pk_mul_f32 v[30:31], v[30:31], v[32:33]
	v_pk_mul_f32 v[32:33], v[22:23], v[22:23]
	v_pk_mul_f32 v[30:31], v[34:35], v[30:31]
	v_pk_mul_f32 v[32:33], v[32:33], s[0:1] op_sel_hi:[1,0]
	v_pk_mul_f32 v[34:35], v[20:21], v[30:31]
	v_pk_fma_f32 v[30:31], v[20:21], v[30:31], v[20:21] neg_lo:[1,0,0] neg_hi:[1,0,0]
	v_exp_f32_e32 v32, v32
	v_cndmask_b32_e32 v20, v30, v34, vcc
	v_cmp_gt_f32_e32 vcc, 0, v21
	v_and_b32_e32 v30, 0x7fffffff, v22
	v_exp_f32_e32 v33, v33
	v_cndmask_b32_e32 v21, v31, v35, vcc
	v_and_b32_e32 v31, 0x7fffffff, v23
	v_pk_fma_f32 v[30:31], v[30:31], s[28:29], 1.0 op_sel_hi:[1,0,0]
	v_cmp_gt_f32_e32 vcc, 0, v22
	v_rcp_f32_e32 v30, v30
	v_rcp_f32_e32 v31, v31
	s_nop 0
	v_pk_fma_f32 v[34:35], v[30:31], s[30:31], v[28:29] op_sel_hi:[1,0,0]
	s_nop 0
	v_pk_fma_f32 v[34:35], v[30:31], v[34:35], s[36:37] op_sel_hi:[1,1,0]
	s_nop 0
	v_pk_fma_f32 v[34:35], v[30:31], v[34:35], s[80:81] op_sel_hi:[1,1,0]
	s_nop 0
	v_pk_fma_f32 v[34:35], v[30:31], v[34:35], s[64:65] op_sel_hi:[1,1,0]
	s_nop 0
	v_pk_mul_f32 v[30:31], v[30:31], v[34:35]
	v_pk_mul_f32 v[34:35], v[16:17], v[16:17]
	v_pk_mul_f32 v[30:31], v[32:33], v[30:31]
	v_pk_mul_f32 v[34:35], v[34:35], s[0:1] op_sel_hi:[1,0]
	v_pk_mul_f32 v[32:33], v[22:23], v[30:31]
	v_pk_fma_f32 v[30:31], v[22:23], v[30:31], v[22:23] neg_lo:[1,0,0] neg_hi:[1,0,0]
	v_exp_f32_e32 v34, v34
	v_cndmask_b32_e32 v22, v30, v32, vcc
	v_cmp_gt_f32_e32 vcc, 0, v23
	v_and_b32_e32 v30, 0x7fffffff, v16
	v_exp_f32_e32 v35, v35
	v_cndmask_b32_e32 v23, v31, v33, vcc
	v_and_b32_e32 v31, 0x7fffffff, v17
	v_pk_fma_f32 v[30:31], v[30:31], s[28:29], 1.0 op_sel_hi:[1,0,0]
	v_cmp_gt_f32_e32 vcc, 0, v16
	v_rcp_f32_e32 v30, v30
	v_rcp_f32_e32 v31, v31
	s_nop 0
	v_pk_fma_f32 v[32:33], v[30:31], s[30:31], v[28:29] op_sel_hi:[1,0,0]
	s_nop 0
	v_pk_fma_f32 v[32:33], v[30:31], v[32:33], s[36:37] op_sel_hi:[1,1,0]
	s_nop 0
	v_pk_fma_f32 v[32:33], v[30:31], v[32:33], s[80:81] op_sel_hi:[1,1,0]
	s_nop 0
	v_pk_fma_f32 v[32:33], v[30:31], v[32:33], s[64:65] op_sel_hi:[1,1,0]
	s_nop 0
	v_pk_mul_f32 v[30:31], v[30:31], v[32:33]
	v_pk_mul_f32 v[32:33], v[18:19], v[18:19]
	v_pk_mul_f32 v[30:31], v[34:35], v[30:31]
	s_nop 0
	v_pk_mul_f32 v[34:35], v[16:17], v[30:31]
	v_pk_fma_f32 v[30:31], v[16:17], v[30:31], v[16:17] neg_lo:[1,0,0] neg_hi:[1,0,0]
	s_nop 0
	v_cndmask_b32_e32 v16, v30, v34, vcc
	v_cmp_gt_f32_e32 vcc, 0, v17
	v_and_b32_e32 v30, 0x7fffffff, v18
	s_nop 0
	v_cndmask_b32_e32 v17, v31, v35, vcc
	v_and_b32_e32 v31, 0x7fffffff, v19
	v_pk_fma_f32 v[30:31], v[30:31], s[28:29], 1.0 op_sel_hi:[1,0,0]
	v_cmp_gt_f32_e32 vcc, 0, v18
	v_rcp_f32_e32 v30, v30
	v_rcp_f32_e32 v31, v31
	s_nop 0
	v_pk_fma_f32 v[28:29], v[30:31], s[30:31], v[28:29] op_sel_hi:[1,0,0]
	s_nop 0
	v_pk_fma_f32 v[28:29], v[30:31], v[28:29], s[36:37] op_sel_hi:[1,1,0]
	s_nop 0
	v_pk_fma_f32 v[28:29], v[30:31], v[28:29], s[80:81] op_sel_hi:[1,1,0]
	s_nop 0
	v_pk_fma_f32 v[28:29], v[30:31], v[28:29], s[64:65] op_sel_hi:[1,1,0]
	s_nop 0
	v_pk_mul_f32 v[28:29], v[30:31], v[28:29]
	v_pk_mul_f32 v[30:31], v[32:33], s[0:1] op_sel_hi:[1,0]
	s_nop 0
	v_exp_f32_e32 v30, v30
	v_exp_f32_e32 v31, v31
	s_nop 0
	v_pk_mul_f32 v[28:29], v[30:31], v[28:29]
	s_nop 0
	v_pk_mul_f32 v[30:31], v[18:19], v[28:29]
	v_pk_fma_f32 v[28:29], v[18:19], v[28:29], v[18:19] neg_lo:[1,0,0] neg_hi:[1,0,0]
	s_nop 0
	v_cndmask_b32_e32 v18, v28, v30, vcc
	v_cmp_gt_f32_e32 vcc, 0, v19
	s_nop 1
	v_cndmask_b32_e32 v19, v29, v31, vcc

; __device__ __forceinline__ unsigned cvt_pk_bf16(float lo, float hi) { unsigned r; asm volatile("v_cvt_pk_bf16_f32 %0, %1, %2" : "=v"(r) : "v"(lo), "v"(hi)); return r; }
;     __device__ __forceinline__ void operator()(const f32x4 (&acc)[2][2][4][2], const Unit& u, int wr, int wc, int fr, int fq) const {
;     ...
;                     u32x4 w; w.x = cvt_pk_bf16(v0[0], v0[1]); w.y = cvt_pk_bf16(v0[2], v0[3]); w.z = cvt_pk_bf16(v1[0], v1[1]); w.w = cvt_pk_bf16(v1[2], v1[3]);
;                     *(u32x4*)(rowp + bj * HALF) = w; }
;                 if (do_stat) { s1 += __shfl_xor(s1, 16); s1 += __shfl_xor(s1, 32); s2 += __shfl_xor(s2, 16); s2 += __shfl_xor(s2, 32);
;                     if (fq == 0) *(f32x2*)(vstat + ((size_t)(row0 + ai * HALF + m * 16) * 8 + (u.pn - vstat_pn0) * 4 + wc) * 2) = (f32x2){s1, s2}; }
.LBB0_384:
	s_and_b64 vcc, exec, s[44:45]
	v_cvt_pk_bf16_f32 v20, v20, v21
	v_cvt_pk_bf16_f32 v21, v22, v23
	v_cvt_pk_bf16_f32 v22, v16, v17
	v_cvt_pk_bf16_f32 v23, v18, v19
	global_store_dwordx4 v[26:27], v[20:23], off offset:256 nt
	s_cbranch_vccnz .LBB0_388
	v_cmp_lt_i32_e32 vcc, v120, v119
	s_nop 1
	v_cndmask_b32_e32 v16, v252, v120, vcc
	v_lshlrev_b32_e32 v17, 2, v16
	ds_bpermute_b32 v16, v17, v28
	ds_bpermute_b32 v17, v17, v29
	v_cmp_lt_i32_e32 vcc, v118, v119
	s_waitcnt lgkmcnt(0)
	v_pk_add_f32 v[16:17], v[28:29], v[16:17]
	v_cndmask_b32_e32 v18, v252, v118, vcc
	v_lshlrev_b32_e32 v19, 2, v18
	ds_bpermute_b32 v18, v19, v16
	ds_bpermute_b32 v19, v19, v17
	s_and_saveexec_b64 s[0:1], s[38:39]
	s_cbranch_execz .LBB0_387
	s_lshl_b32 s4, s60, 2
	s_add_i32 s4, s4, -16
	s_waitcnt lgkmcnt(0)
	v_pk_add_f32 v[16:17], v[16:17], v[18:19]
	v_ashrrev_i32_e32 v113, 31, v112
	v_mov_b32_e32 v18, s4
	v_mov_b32_e32 v19, v193
	v_lshl_add_u64 v[18:19], v[112:113], 3, v[18:19]
	v_or_b32_e32 v18, s83, v18
	v_lshl_add_u64 v[18:19], v[18:19], 3, s[20:21]
	v_add_co_u32_e32 v18, vcc, 0x2000, v18
	s_nop 1
	v_addc_co_u32_e32 v19, vcc, 0, v19, vcc
	global_store_dwordx2 v[18:19], v[16:17], off offset:2048

; __device__ __forceinline__ unsigned cvt_pk_bf16(float lo, float hi) { unsigned r; asm volatile("v_cvt_pk_bf16_f32 %0, %1, %2" : "=v"(r) : "v"(lo), "v"(hi)); return r; }
; __device__ __forceinline__ f32x2 gelu_pk(f32x2 v) {
;     const f32x2 av = __builtin_elementwise_abs(v), d = av * 0.2316418882f + 1.0f;
;     f32x2 t; t.x = __builtin_amdgcn_rcpf(d.x); t.y = __builtin_amdgcn_rcpf(d.y);
;     f32x2 q = t * 0.5307027145f + (-0.7265760135f); q = q * t + 0.7107068705f; q = q * t + (-0.142248368f); q = q * t + 0.127414796f; q = q * t;
;     const f32x2 s = (v * v) * (-0.72134752044f);
;     f32x2 e; e.x = __builtin_amdgcn_exp2f(s.x); e.y = __builtin_amdgcn_exp2f(s.y);
;     const f32x2 m = v * (q * e), r = v - m;
;     f32x2 o; o.x = v.x < 0.f ? m.x : r.x; o.y = v.y < 0.f ? m.y : r.y; return o;
;     __device__ __forceinline__ void operator()(const f32x4 (&acc)[2][2][4][2], const Unit& u, int wr, int wc, int fr, int fq) const {
;     ...
;                 for (int bj = 0; bj < 2; ++bj) { f32x4 v0 = acc[ai][bj][m][0] * sc, v1 = acc[ai][bj][m][1] * sc;
;                     if (do_gelu) { f32x2 a = gelu_pk((f32x2){v0[0], v0[1]}), b = gelu_pk((f32x2){v0[2], v0[3]}), c = gelu_pk((f32x2){v1[0], v1[1]}), d = gelu_pk((f32x2){v1[2], v1[3]});
;                         v0 = (f32x4){a.x, a.y, b.x, b.y}; v1 = (f32x4){c.x, c.y, d.x, d.y}; }
;                     if (do_stat) { s1 += ((v0[0] + v0[1]) + (v0[2] + v0[3])) + ((v1[0] + v1[1]) + (v1[2] + v1[3]));
;                         s2 += ((v0[0] * v0[0] + v0[1] * v0[1]) + (v0[2] * v0[2] + v0[3] * v0[3])) + ((v1[0] * v1[0] + v1[1] * v1[1]) + (v1[2] * v1[2] + v1[3] * v1[3])); }
;                     u32x4 w; w.x = cvt_pk_bf16(v0[0], v0[1]); w.y = cvt_pk_bf16(v0[2], v0[3]); w.z = cvt_pk_bf16(v1[0], v1[1]); w.w = cvt_pk_bf16(v1[2], v1[3]);
;                     *(u32x4*)(rowp + bj * HALF) = w; }
.LBB0_394:
	v_lshl_add_u64 v[10:11], s[16:17], 0, v[150:151]
	v_lshl_add_u64 v[10:11], v[10:11], 0, s[86:87]
	v_lshl_add_u64 v[10:11], v[10:11], 0, v[192:193]
	v_cvt_pk_bf16_f32 v12, v12, v13
	v_cvt_pk_bf16_f32 v13, v14, v15
	v_mov_b32_e32 v157, v156
	v_cvt_pk_bf16_f32 v14, v18, v19
	v_cvt_pk_bf16_f32 v15, v16, v17
	global_store_dwordx4 v[10:11], v[12:15], off nt
	v_pk_mul_f32 v[4:5], v[4:5], v[156:157]
	s_and_b64 vcc, exec, s[42:43]
	v_mov_b32_e32 v12, v156
	v_mov_b32_e32 v13, v156
	v_pk_mul_f32 v[6:7], v[6:7], v[12:13]
	v_pk_mul_f32 v[2:3], v[2:3], v[12:13]
	v_pk_mul_f32 v[0:1], v[0:1], v[156:157]
	s_cbranch_vccnz .LBB0_396
	v_and_b32_e32 v13, 0x7fffffff, v5
	v_and_b32_e32 v12, 0x7fffffff, v4
	v_pk_fma_f32 v[12:13], v[12:13], s[28:29], 1.0 op_sel_hi:[1,0,0]
	s_mov_b32 s0, 0xbf3a00e3
	v_rcp_f32_e32 v14, v12
	v_rcp_f32_e32 v15, v13
	v_mov_b64_e32 v[12:13], s[0:1]
	v_pk_mul_f32 v[18:19], v[4:5], v[4:5]
	s_mov_b32 s0, 0xbf38aa3b
	v_pk_fma_f32 v[16:17], v[14:15], s[30:31], v[12:13] op_sel_hi:[1,0,0]
	v_pk_mul_f32 v[18:19], v[18:19], s[0:1] op_sel_hi:[1,0]
	v_pk_fma_f32 v[16:17], v[14:15], v[16:17], s[36:37] op_sel_hi:[1,1,0]
	v_exp_f32_e32 v18, v18
	v_exp_f32_e32 v19, v19
	v_pk_fma_f32 v[16:17], v[14:15], v[16:17], s[80:81] op_sel_hi:[1,1,0]
	v_cmp_gt_f32_e32 vcc, 0, v4
	v_pk_fma_f32 v[16:17], v[14:15], v[16:17], s[64:65] op_sel_hi:[1,1,0]
	s_nop 0
	v_pk_mul_f32 v[14:15], v[14:15], v[16:17]
	v_pk_mul_f32 v[16:17], v[6:7], v[6:7]
	v_pk_mul_f32 v[14:15], v[18:19], v[14:15]
	v_pk_mul_f32 v[16:17], v[16:17], s[0:1] op_sel_hi:[1,0]
	v_pk_mul_f32 v[18:19], v[4:5], v[14:15]
	v_pk_fma_f32 v[14:15], v[4:5], v[14:15], v[4:5] neg_lo:[1,0,0] neg_hi:[1,0,0]
	v_exp_f32_e32 v16, v16
	v_cndmask_b32_e32 v4, v14, v18, vcc
	v_cmp_gt_f32_e32 vcc, 0, v5
	v_and_b32_e32 v14, 0x7fffffff, v6
	v_exp_f32_e32 v17, v17
	v_cndmask_b32_e32 v5, v15, v19, vcc
	v_and_b32_e32 v15, 0x7fffffff, v7
	v_pk_fma_f32 v[14:15], v[14:15], s[28:29], 1.0 op_sel_hi:[1,0,0]
	v_cmp_gt_f32_e32 vcc, 0, v6
	v_rcp_f32_e32 v14, v14
	v_rcp_f32_e32 v15, v15
	s_nop 0
	v_pk_fma_f32 v[18:19], v[14:15], s[30:31], v[12:13] op_sel_hi:[1,0,0]
	s_nop 0
	v_pk_fma_f32 v[18:19], v[14:15], v[18:19], s[36:37] op_sel_hi:[1,1,0]
	s_nop 0
	v_pk_fma_f32 v[18:19], v[14:15], v[18:19], s[80:81] op_sel_hi:[1,1,0]
	s_nop 0
	v_pk_fma_f32 v[18:19], v[14:15], v[18:19], s[64:65] op_sel_hi:[1,1,0]
	s_nop 0
	v_pk_mul_f32 v[14:15], v[14:15], v[18:19]
	v_pk_mul_f32 v[18:19], v[0:1], v[0:1]
	v_pk_mul_f32 v[14:15], v[16:17], v[14:15]
	v_pk_mul_f32 v[18:19], v[18:19], s[0:1] op_sel_hi:[1,0]
	v_pk_mul_f32 v[16:17], v[6:7], v[14:15]
	v_pk_fma_f32 v[14:15], v[6:7], v[14:15], v[6:7] neg_lo:[1,0,0] neg_hi:[1,0,0]
	v_exp_f32_e32 v18, v18
	v_cndmask_b32_e32 v6, v14, v16, vcc
	v_cmp_gt_f32_e32 vcc, 0, v7
	v_and_b32_e32 v14, 0x7fffffff, v0
	v_exp_f32_e32 v19, v19
	v_cndmask_b32_e32 v7, v15, v17, vcc
	v_and_b32_e32 v15, 0x7fffffff, v1
	v_pk_fma_f32 v[14:15], v[14:15], s[28:29], 1.0 op_sel_hi:[1,0,0]
	v_cmp_gt_f32_e32 vcc, 0, v0
	v_rcp_f32_e32 v14, v14
	v_rcp_f32_e32 v15, v15
	s_nop 0
	v_pk_fma_f32 v[16:17], v[14:15], s[30:31], v[12:13] op_sel_hi:[1,0,0]
	s_nop 0
	v_pk_fma_f32 v[16:17], v[14:15], v[16:17], s[36:37] op_sel_hi:[1,1,0]
	s_nop 0
	v_pk_fma_f32 v[16:17], v[14:15], v[16:17], s[80:81] op_sel_hi:[1,1,0]
	s_nop 0
	v_pk_fma_f32 v[16:17], v[14:15], v[16:17], s[64:65] op_sel_hi:[1,1,0]
	s_nop 0
	v_pk_mul_f32 v[14:15], v[14:15], v[16:17]
	v_pk_mul_f32 v[16:17], v[2:3], v[2:3]
	v_pk_mul_f32 v[14:15], v[18:19], v[14:15]
	s_nop 0
	v_pk_mul_f32 v[18:19], v[0:1], v[14:15]
	v_pk_fma_f32 v[14:15], v[0:1], v[14:15], v[0:1] neg_lo:[1,0,0] neg_hi:[1,0,0]
	s_nop 0
	v_cndmask_b32_e32 v0, v14, v18, vcc
	v_cmp_gt_f32_e32 vcc, 0, v1
	v_and_b32_e32 v14, 0x7fffffff, v2
	s_nop 0
	v_cndmask_b32_e32 v1, v15, v19, vcc
	v_and_b32_e32 v15, 0x7fffffff, v3
	v_pk_fma_f32 v[14:15], v[14:15], s[28:29], 1.0 op_sel_hi:[1,0,0]
	v_cmp_gt_f32_e32 vcc, 0, v2
	v_rcp_f32_e32 v14, v14
	v_rcp_f32_e32 v15, v15
	s_nop 0
	v_pk_fma_f32 v[12:13], v[14:15], s[30:31], v[12:13] op_sel_hi:[1,0,0]
	s_nop 0
	v_pk_fma_f32 v[12:13], v[14:15], v[12:13], s[36:37] op_sel_hi:[1,1,0]
	s_nop 0
	v_pk_fma_f32 v[12:13], v[14:15], v[12:13], s[80:81] op_sel_hi:[1,1,0]
	s_nop 0
	v_pk_fma_f32 v[12:13], v[14:15], v[12:13], s[64:65] op_sel_hi:[1,1,0]
	s_nop 0
	v_pk_mul_f32 v[12:13], v[14:15], v[12:13]
	v_pk_mul_f32 v[14:15], v[16:17], s[0:1] op_sel_hi:[1,0]
	s_nop 0
	v_exp_f32_e32 v14, v14
	v_exp_f32_e32 v15, v15
	s_nop 0
	v_pk_mul_f32 v[12:13], v[14:15], v[12:13]
	s_nop 0
	v_pk_mul_f32 v[14:15], v[2:3], v[12:13]
	v_pk_fma_f32 v[12:13], v[2:3], v[12:13], v[2:3] neg_lo:[1,0,0] neg_hi:[1,0,0]
	s_nop 0
	v_cndmask_b32_e32 v2, v12, v14, vcc
	v_cmp_gt_f32_e32 vcc, 0, v3
	s_nop 1
	v_cndmask_b32_e32 v3, v13, v15, vcc

; __device__ __forceinline__ unsigned cvt_pk_bf16(float lo, float hi) { unsigned r; asm volatile("v_cvt_pk_bf16_f32 %0, %1, %2" : "=v"(r) : "v"(lo), "v"(hi)); return r; }
;     __device__ __forceinline__ void operator()(const f32x4 (&acc)[2][2][4][2], const Unit& u, int wr, int wc, int fr, int fq) const {
;     ...
;                     u32x4 w; w.x = cvt_pk_bf16(v0[0], v0[1]); w.y = cvt_pk_bf16(v0[2], v0[3]); w.z = cvt_pk_bf16(v1[0], v1[1]); w.w = cvt_pk_bf16(v1[2], v1[3]);
;                     *(u32x4*)(rowp + bj * HALF) = w; }
;                 if (do_stat) { s1 += __shfl_xor(s1, 16); s1 += __shfl_xor(s1, 32); s2 += __shfl_xor(s2, 16); s2 += __shfl_xor(s2, 32);
;                     if (fq == 0) *(f32x2*)(vstat + ((size_t)(row0 + ai * HALF + m * 16) * 8 + (u.pn - vstat_pn0) * 4 + wc) * 2) = (f32x2){s1, s2}; }
.LBB0_401:
	s_and_b64 vcc, exec, s[44:45]
	v_cvt_pk_bf16_f32 v4, v4, v5
	v_cvt_pk_bf16_f32 v5, v6, v7
	v_cvt_pk_bf16_f32 v6, v0, v1
	v_cvt_pk_bf16_f32 v7, v2, v3
	global_store_dwordx4 v[10:11], v[4:7], off offset:256 nt
	s_cbranch_vccnz .LBB0_405
	v_cmp_lt_i32_e32 vcc, v120, v119
	s_nop 1
	v_cndmask_b32_e32 v0, v252, v120, vcc
	v_lshlrev_b32_e32 v1, 2, v0
	ds_bpermute_b32 v0, v1, v12
	ds_bpermute_b32 v1, v1, v13
	v_cmp_lt_i32_e32 vcc, v118, v119
	s_waitcnt lgkmcnt(0)
	v_pk_add_f32 v[0:1], v[12:13], v[0:1]
	v_cndmask_b32_e32 v2, v252, v118, vcc
	v_lshlrev_b32_e32 v3, 2, v2
	ds_bpermute_b32 v2, v3, v0
	ds_bpermute_b32 v3, v3, v1
	s_and_saveexec_b64 s[0:1], s[38:39]
	s_cbranch_execz .LBB0_404
	s_lshl_b32 s4, s60, 2
	s_add_i32 s4, s4, -16
	s_waitcnt lgkmcnt(0)
	v_pk_add_f32 v[0:1], v[0:1], v[2:3]
	v_ashrrev_i32_e32 v113, 31, v112
	v_mov_b32_e32 v2, s4
	v_mov_b32_e32 v3, v193
	v_lshl_add_u64 v[2:3], v[112:113], 3, v[2:3]
	v_or_b32_e32 v2, s83, v2
	v_lshl_add_u64 v[2:3], v[2:3], 3, s[20:21]
	v_add_co_u32_e32 v2, vcc, 0x2000, v2
	s_nop 1
	v_addc_co_u32_e32 v3, vcc, 0, v3, vcc
	global_store_dwordx2 v[2:3], v[0:1], off offset:3072

; #define PG8_LAS __attribute__((address_space(3)))
; __device__ __forceinline__ unsigned cvt_pk_bf16(float lo, float hi) { unsigned r; asm volatile("v_cvt_pk_bf16_f32 %0, %1, %2" : "=v"(r) : "v"(lo), "v"(hi)); return r; }
;     __device__ __forceinline__ void operator()(f32x4 (&acc)[2][2][4][2], const Unit& u, int wr, int wc, int fr, int fq) const {
;     ...
;         asm volatile("s_waitcnt lgkmcnt(0)" ::: "memory"); __builtin_amdgcn_s_barrier(); asm volatile("" ::: "memory");
; #pragma unroll
;         for (int ai = 0; ai < 2; ++ai)
; #pragma unroll
;             for (int m = 0; m < 4; ++m) { const int r = ai * HALF + wr * 64 + m * 16 + fr; const f32x4 s4 = *(const PG8_LAS f32x4*)(xch + 1024 + r * 4);
;                 const float inv = 1.0f / ((s4[0] + s4[1]) + (s4[2] + s4[3]));
;                 bf16_t* rowp = P + (size_t)(u.pm >> 5) * bgap + (size_t)(u.pm * BM + r) * 1024 + u.pn * BM + wc * 32 + 8 * fq;
; #pragma unroll
;                 for (int bj = 0; bj < 2; ++bj) { const f32x4 v0 = acc[ai][bj][m][0] * inv, v1 = acc[ai][bj][m][1] * inv;
;                     u32x4 w; w.x = cvt_pk_bf16(v0[0], v0[1]); w.y = cvt_pk_bf16(v0[2], v0[3]); w.z = cvt_pk_bf16(v1[0], v1[1]); w.w = cvt_pk_bf16(v1[2], v1[3]);
;                     *(u32x4*)(rowp + bj * HALF) = w; }
.LBB0_722:
	s_or_b64 exec, exec, s[22:23]
	s_waitcnt lgkmcnt(0)
	s_barrier
	v_add_u32_e32 v128, s2, v214
	s_waitcnt lgkmcnt(0)
	ds_read_b128 v[128:131], v128
	s_ashr_i32 s17, s67, 5
	s_lshl_b32 s24, s66, 8
	s_ashr_i32 s25, s24, 31
	s_waitcnt lgkmcnt(0)
	v_mov_b32_e32 v132, v129
	v_mov_b32_e32 v133, v130
	v_mov_b32_e32 v129, v131
	v_pk_add_f32 v[128:129], v[132:133], v[128:129]
	s_nop 0
	v_add_f32_e32 v128, v128, v129
	v_div_scale_f32 v129, s[22:23], v128, v128, 1.0
	v_rcp_f32_e32 v130, v129
	s_mul_hi_i32 s23, s17, 0x1c00000
	s_mul_i32 s17, s17, 0x1c00000
	s_add_u32 s22, s47, s17
	v_fma_f32 v131, -v129, v130, 1.0
	v_fmac_f32_e32 v130, v131, v130
	v_div_scale_f32 v131, vcc, 1.0, v128, 1.0
	v_mul_f32_e32 v132, v131, v130
	v_fma_f32 v133, -v129, v132, v131
	v_fmac_f32_e32 v132, v133, v130
	v_fma_f32 v129, -v129, v132, v131
	v_div_fmas_f32 v129, v129, v130, v132
	v_add_u32_e32 v130, s13, v211
	v_ashrrev_i32_e32 v131, 31, v130
	s_addc_u32 s23, s60, s23
	v_lshlrev_b64 v[130:131], 11, v[130:131]
	v_lshl_add_u64 v[130:131], s[22:23], 0, v[130:131]
	s_lshl_b64 s[24:25], s[24:25], 1
	v_div_fixup_f32 v128, v129, v128, 1.0
	v_lshl_add_u64 v[130:131], v[130:131], 0, s[24:25]
	v_lshl_add_u64 v[130:131], v[130:131], 0, s[86:87]
	v_pk_mul_f32 v[118:119], v[118:119], v[128:129] op_sel_hi:[1,0]
	v_pk_mul_f32 v[110:111], v[110:111], v[128:129] op_sel_hi:[1,0]
	v_lshl_add_u64 v[130:131], v[130:131], 0, v[192:193]
	v_pk_mul_f32 v[124:125], v[124:125], v[128:129] op_sel_hi:[1,0]
	v_pk_mul_f32 v[132:133], v[116:117], v[128:129] op_sel_hi:[1,0]
	v_cvt_pk_bf16_f32 v116, v110, v111
	v_cvt_pk_bf16_f32 v117, v118, v119
	v_pk_mul_f32 v[110:111], v[122:123], v[128:129] op_sel_hi:[1,0]
	v_cvt_pk_bf16_f32 v118, v132, v133
	v_cvt_pk_bf16_f32 v119, v124, v125
	v_pk_mul_f32 v[108:109], v[108:109], v[128:129] op_sel_hi:[1,0]
	global_store_dwordx4 v[130:131], v[116:119], off nt
	v_cvt_pk_bf16_f32 v108, v108, v109
	v_cvt_pk_bf16_f32 v109, v110, v111
	s_nop 1
	v_pk_mul_f32 v[116:117], v[126:127], v[128:129] op_sel_hi:[1,0]
	v_pk_mul_f32 v[118:119], v[120:121], v[128:129] op_sel_hi:[1,0]
	s_nop 0
	v_cvt_pk_bf16_f32 v110, v118, v119
	v_cvt_pk_bf16_f32 v111, v116, v117
	global_store_dwordx4 v[130:131], v[108:111], off offset:256 nt
	ds_read_b128 v[108:111], v228
	s_waitcnt lgkmcnt(0)
	v_mov_b32_e32 v116, v109
	v_mov_b32_e32 v117, v110
	v_mov_b32_e32 v109, v111
	v_pk_add_f32 v[108:109], v[116:117], v[108:109]
	s_nop 0
	v_add_f32_e32 v108, v108, v109
	v_div_scale_f32 v109, s[26:27], v108, v108, 1.0
	v_rcp_f32_e32 v110, v109
	s_nop 0
	v_fma_f32 v111, -v109, v110, 1.0
	v_fmac_f32_e32 v110, v111, v110
	v_div_scale_f32 v111, vcc, 1.0, v108, 1.0
	v_mul_f32_e32 v116, v111, v110
	v_fma_f32 v117, -v109, v116, v111
	v_fmac_f32_e32 v116, v117, v110
	v_fma_f32 v109, -v109, v116, v111
	v_div_fmas_f32 v109, v109, v110, v116
	v_div_fixup_f32 v110, v109, v108, 1.0
	v_add_u32_e32 v108, s13, v217
	v_ashrrev_i32_e32 v109, 31, v108
	v_lshlrev_b64 v[108:109], 11, v[108:109]
	v_lshl_add_u64 v[108:109], s[22:23], 0, v[108:109]
	v_lshl_add_u64 v[108:109], v[108:109], 0, s[24:25]
	v_lshl_add_u64 v[108:109], v[108:109], 0, s[86:87]
	v_pk_mul_f32 v[94:95], v[94:95], v[110:111] op_sel_hi:[1,0]
	v_lshl_add_u64 v[116:117], v[108:109], 0, v[192:193]
	v_pk_mul_f32 v[108:109], v[106:107], v[110:111] op_sel_hi:[1,0]
	v_pk_mul_f32 v[100:101], v[100:101], v[110:111] op_sel_hi:[1,0]
	v_cvt_pk_bf16_f32 v106, v94, v95
	v_pk_mul_f32 v[94:95], v[104:105], v[110:111] op_sel_hi:[1,0]
	v_pk_mul_f32 v[92:93], v[92:93], v[110:111] op_sel_hi:[1,0]
	v_pk_mul_f32 v[112:113], v[112:113], v[110:111] op_sel_hi:[1,0]
	v_cvt_pk_bf16_f32 v107, v108, v109
	v_cvt_pk_bf16_f32 v108, v100, v101
	v_pk_mul_f32 v[100:101], v[114:115], v[110:111] op_sel_hi:[1,0]
	v_cvt_pk_bf16_f32 v109, v112, v113
	global_store_dwordx4 v[116:117], v[106:109], off nt
	v_pk_mul_f32 v[102:103], v[102:103], v[110:111] op_sel_hi:[1,0]
	v_cvt_pk_bf16_f32 v92, v92, v93
	v_cvt_pk_bf16_f32 v93, v94, v95
	s_nop 0
	v_cvt_pk_bf16_f32 v94, v102, v103
	v_cvt_pk_bf16_f32 v95, v100, v101
	global_store_dwordx4 v[116:117], v[92:95], off offset:256 nt
	ds_read_b128 v[92:95], v229
	s_waitcnt lgkmcnt(0)
	v_mov_b32_e32 v100, v93
	v_mov_b32_e32 v101, v94
	v_mov_b32_e32 v93, v95
	v_pk_add_f32 v[92:93], v[100:101], v[92:93]
	s_nop 0
	v_add_f32_e32 v92, v92, v93
	v_div_scale_f32 v93, s[26:27], v92, v92, 1.0
	v_rcp_f32_e32 v94, v93
	s_nop 0
	v_fma_f32 v95, -v93, v94, 1.0
	v_fmac_f32_e32 v94, v95, v94
	v_div_scale_f32 v95, vcc, 1.0, v92, 1.0
	v_mul_f32_e32 v100, v95, v94
	v_fma_f32 v101, -v93, v100, v95
	v_fmac_f32_e32 v100, v101, v94
	v_fma_f32 v93, -v93, v100, v95
	v_div_fmas_f32 v93, v93, v94, v100
	v_div_fixup_f32 v94, v93, v92, 1.0
	v_add_u32_e32 v92, s13, v218
	v_ashrrev_i32_e32 v93, 31, v92
	v_lshlrev_b64 v[92:93], 11, v[92:93]
	v_lshl_add_u64 v[92:93], s[22:23], 0, v[92:93]
	v_lshl_add_u64 v[92:93], v[92:93], 0, s[24:25]
	v_lshl_add_u64 v[92:93], v[92:93], 0, s[86:87]
	v_pk_mul_f32 v[78:79], v[78:79], v[94:95] op_sel_hi:[1,0]
	v_lshl_add_u64 v[100:101], v[92:93], 0, v[192:193]
	v_pk_mul_f32 v[92:93], v[90:91], v[94:95] op_sel_hi:[1,0]
	v_pk_mul_f32 v[84:85], v[84:85], v[94:95] op_sel_hi:[1,0]
	v_cvt_pk_bf16_f32 v90, v78, v79
	v_pk_mul_f32 v[78:79], v[88:89], v[94:95] op_sel_hi:[1,0]
	v_pk_mul_f32 v[76:77], v[76:77], v[94:95] op_sel_hi:[1,0]
	v_pk_mul_f32 v[96:97], v[96:97], v[94:95] op_sel_hi:[1,0]
	v_cvt_pk_bf16_f32 v91, v92, v93
	v_cvt_pk_bf16_f32 v92, v84, v85
	v_pk_mul_f32 v[84:85], v[98:99], v[94:95] op_sel_hi:[1,0]
	v_cvt_pk_bf16_f32 v93, v96, v97
	global_store_dwordx4 v[100:101], v[90:93], off nt
	v_pk_mul_f32 v[86:87], v[86:87], v[94:95] op_sel_hi:[1,0]
	v_cvt_pk_bf16_f32 v76, v76, v77
	v_cvt_pk_bf16_f32 v77, v78, v79
	s_nop 0
	v_cvt_pk_bf16_f32 v78, v86, v87
	v_cvt_pk_bf16_f32 v79, v84, v85
	global_store_dwordx4 v[100:101], v[76:79], off offset:256 nt
	ds_read_b128 v[76:79], v230
	s_waitcnt lgkmcnt(0)
; #define PG8_LAS __attribute__((address_space(3)))
; __device__ __forceinline__ unsigned cvt_pk_bf16(float lo, float hi) { unsigned r; asm volatile("v_cvt_pk_bf16_f32 %0, %1, %2" : "=v"(r) : "v"(lo), "v"(hi)); return r; }
;     __device__ __forceinline__ void operator()(f32x4 (&acc)[2][2][4][2], const Unit& u, int wr, int wc, int fr, int fq) const {
;     ...
;             for (int m = 0; m < 4; ++m) { const int r = ai * HALF + wr * 64 + m * 16 + fr; const f32x4 s4 = *(const PG8_LAS f32x4*)(xch + 1024 + r * 4);
;                 const float inv = 1.0f / ((s4[0] + s4[1]) + (s4[2] + s4[3]));
;                 bf16_t* rowp = P + (size_t)(u.pm >> 5) * bgap + (size_t)(u.pm * BM + r) * 1024 + u.pn * BM + wc * 32 + 8 * fq;
; #pragma unroll
;                 for (int bj = 0; bj < 2; ++bj) { const f32x4 v0 = acc[ai][bj][m][0] * inv, v1 = acc[ai][bj][m][1] * inv;
;                     u32x4 w; w.x = cvt_pk_bf16(v0[0], v0[1]); w.y = cvt_pk_bf16(v0[2], v0[3]); w.z = cvt_pk_bf16(v1[0], v1[1]); w.w = cvt_pk_bf16(v1[2], v1[3]);
;                     *(u32x4*)(rowp + bj * HALF) = w; }
	v_mov_b32_e32 v84, v77
	v_mov_b32_e32 v85, v78
	v_mov_b32_e32 v77, v79
	v_pk_add_f32 v[76:77], v[84:85], v[76:77]
	s_nop 0
	v_add_f32_e32 v76, v76, v77
	v_div_scale_f32 v77, s[26:27], v76, v76, 1.0
	v_rcp_f32_e32 v78, v77
	s_nop 0
	v_fma_f32 v79, -v77, v78, 1.0
	v_fmac_f32_e32 v78, v79, v78
	v_div_scale_f32 v79, vcc, 1.0, v76, 1.0
	v_mul_f32_e32 v84, v79, v78
	v_fma_f32 v85, -v77, v84, v79
	v_fmac_f32_e32 v84, v85, v78
	v_fma_f32 v77, -v77, v84, v79
	v_div_fmas_f32 v77, v77, v78, v84
	v_div_fixup_f32 v78, v77, v76, 1.0
	v_add_u32_e32 v76, s13, v219
	v_ashrrev_i32_e32 v77, 31, v76
	v_lshlrev_b64 v[76:77], 11, v[76:77]
	v_lshl_add_u64 v[76:77], s[22:23], 0, v[76:77]
	v_lshl_add_u64 v[76:77], v[76:77], 0, s[24:25]
	v_lshl_add_u64 v[76:77], v[76:77], 0, s[86:87]
	v_lshl_add_u64 v[84:85], v[76:77], 0, v[192:193]
	v_pk_mul_f32 v[76:77], v[74:75], v[78:79] op_sel_hi:[1,0]
	v_pk_mul_f32 v[64:65], v[64:65], v[78:79] op_sel_hi:[1,0]
	v_pk_mul_f32 v[68:69], v[68:69], v[78:79] op_sel_hi:[1,0]
	v_pk_mul_f32 v[70:71], v[70:71], v[78:79] op_sel_hi:[1,0]
	v_pk_mul_f32 v[80:81], v[80:81], v[78:79] op_sel_hi:[1,0]
	v_cvt_pk_bf16_f32 v74, v64, v65
	v_cvt_pk_bf16_f32 v75, v76, v77
	v_cvt_pk_bf16_f32 v76, v68, v69
	v_pk_mul_f32 v[64:65], v[72:73], v[78:79] op_sel_hi:[1,0]
	v_cvt_pk_bf16_f32 v77, v80, v81
	global_store_dwordx4 v[84:85], v[74:77], off nt
	v_pk_mul_f32 v[60:61], v[60:61], v[78:79] op_sel_hi:[1,0]
	v_pk_mul_f32 v[72:73], v[82:83], v[78:79] op_sel_hi:[1,0]
	v_cvt_pk_bf16_f32 v68, v60, v61
	v_cvt_pk_bf16_f32 v69, v64, v65
	v_cvt_pk_bf16_f32 v70, v70, v71
	v_add_u32_e32 v60, s2, v216
	v_cvt_pk_bf16_f32 v71, v72, v73
	global_store_dwordx4 v[84:85], v[68:71], off offset:256 nt
	ds_read_b128 v[68:71], v60
	s_waitcnt lgkmcnt(0)
	v_mov_b32_e32 v60, v69
	v_mov_b32_e32 v61, v70
	v_mov_b32_e32 v69, v71
	v_pk_add_f32 v[60:61], v[60:61], v[68:69]
	s_nop 0
	v_add_f32_e32 v60, v60, v61
	v_div_scale_f32 v61, s[26:27], v60, v60, 1.0
	v_rcp_f32_e32 v64, v61
	s_nop 0
	v_fma_f32 v65, -v61, v64, 1.0
	v_fmac_f32_e32 v64, v65, v64
	v_div_scale_f32 v65, vcc, 1.0, v60, 1.0
	v_mul_f32_e32 v68, v65, v64
	v_fma_f32 v69, -v61, v68, v65
	v_fmac_f32_e32 v68, v69, v64
	v_fma_f32 v61, -v61, v68, v65
	v_div_fmas_f32 v61, v61, v64, v68
	v_div_fixup_f32 v64, v61, v60, 1.0
	v_add_u32_e32 v60, s13, v215
	v_ashrrev_i32_e32 v61, 31, v60
	v_lshlrev_b64 v[60:61], 11, v[60:61]
	v_lshl_add_u64 v[60:61], s[22:23], 0, v[60:61]
	v_lshl_add_u64 v[60:61], v[60:61], 0, s[24:25]
	v_lshl_add_u64 v[60:61], v[60:61], 0, s[86:87]
	v_pk_mul_f32 v[46:47], v[46:47], v[64:65] op_sel_hi:[1,0]
	v_lshl_add_u64 v[68:69], v[60:61], 0, v[192:193]
	v_pk_mul_f32 v[60:61], v[58:59], v[64:65] op_sel_hi:[1,0]
	v_pk_mul_f32 v[52:53], v[52:53], v[64:65] op_sel_hi:[1,0]
	v_cvt_pk_bf16_f32 v58, v46, v47
	v_pk_mul_f32 v[46:47], v[56:57], v[64:65] op_sel_hi:[1,0]
	v_pk_mul_f32 v[44:45], v[44:45], v[64:65] op_sel_hi:[1,0]
	v_pk_mul_f32 v[62:63], v[62:63], v[64:65] op_sel_hi:[1,0]
	v_cvt_pk_bf16_f32 v59, v60, v61
	v_cvt_pk_bf16_f32 v60, v52, v53
	v_pk_mul_f32 v[52:53], v[66:67], v[64:65] op_sel_hi:[1,0]
	v_cvt_pk_bf16_f32 v61, v62, v63
	global_store_dwordx4 v[68:69], v[58:61], off nt
	v_pk_mul_f32 v[54:55], v[54:55], v[64:65] op_sel_hi:[1,0]
	v_cvt_pk_bf16_f32 v44, v44, v45
	v_cvt_pk_bf16_f32 v45, v46, v47
	s_nop 0
	v_cvt_pk_bf16_f32 v46, v54, v55
	v_cvt_pk_bf16_f32 v47, v52, v53
	global_store_dwordx4 v[68:69], v[44:47], off offset:256 nt
	ds_read_b128 v[44:47], v231
	s_waitcnt lgkmcnt(0)
	v_mov_b32_e32 v52, v45
	v_mov_b32_e32 v53, v46
	v_mov_b32_e32 v45, v47
	v_pk_add_f32 v[44:45], v[52:53], v[44:45]
	s_nop 0
	v_add_f32_e32 v44, v44, v45
	v_div_scale_f32 v45, s[26:27], v44, v44, 1.0
	v_rcp_f32_e32 v46, v45
	s_nop 0
	v_fma_f32 v47, -v45, v46, 1.0
	v_fmac_f32_e32 v46, v47, v46
	v_div_scale_f32 v47, vcc, 1.0, v44, 1.0
	v_mul_f32_e32 v52, v47, v46
	v_fma_f32 v53, -v45, v52, v47
	v_fmac_f32_e32 v52, v53, v46
	v_fma_f32 v45, -v45, v52, v47
	v_div_fmas_f32 v45, v45, v46, v52
	v_div_fixup_f32 v46, v45, v44, 1.0
	v_add_u32_e32 v44, s13, v220
	v_ashrrev_i32_e32 v45, 31, v44
	v_lshlrev_b64 v[44:45], 11, v[44:45]
	v_lshl_add_u64 v[44:45], s[22:23], 0, v[44:45]
	v_lshl_add_u64 v[44:45], v[44:45], 0, s[24:25]
	v_lshl_add_u64 v[44:45], v[44:45], 0, s[86:87]
	v_pk_mul_f32 v[30:31], v[30:31], v[46:47] op_sel_hi:[1,0]
	v_lshl_add_u64 v[52:53], v[44:45], 0, v[192:193]
	v_pk_mul_f32 v[44:45], v[42:43], v[46:47] op_sel_hi:[1,0]
	v_pk_mul_f32 v[36:37], v[36:37], v[46:47] op_sel_hi:[1,0]
	v_cvt_pk_bf16_f32 v42, v30, v31
	v_pk_mul_f32 v[30:31], v[40:41], v[46:47] op_sel_hi:[1,0]
	v_pk_mul_f32 v[28:29], v[28:29], v[46:47] op_sel_hi:[1,0]
	v_pk_mul_f32 v[48:49], v[48:49], v[46:47] op_sel_hi:[1,0]
	v_cvt_pk_bf16_f32 v43, v44, v45
	v_cvt_pk_bf16_f32 v44, v36, v37
	v_pk_mul_f32 v[36:37], v[50:51], v[46:47] op_sel_hi:[1,0]
	v_cvt_pk_bf16_f32 v45, v48, v49
	global_store_dwordx4 v[52:53], v[42:45], off nt
	v_pk_mul_f32 v[38:39], v[38:39], v[46:47] op_sel_hi:[1,0]
	v_cvt_pk_bf16_f32 v28, v28, v29
	v_cvt_pk_bf16_f32 v29, v30, v31
	s_nop 0
	v_cvt_pk_bf16_f32 v30, v38, v39
	v_cvt_pk_bf16_f32 v31, v36, v37
	global_store_dwordx4 v[52:53], v[28:31], off offset:256 nt
	ds_read_b128 v[28:31], v232
	s_waitcnt lgkmcnt(0)
; #define PG8_LAS __attribute__((address_space(3)))
; __device__ __forceinline__ unsigned cvt_pk_bf16(float lo, float hi) { unsigned r; asm volatile("v_cvt_pk_bf16_f32 %0, %1, %2" : "=v"(r) : "v"(lo), "v"(hi)); return r; }
; #define PG8_BAR __builtin_amdgcn_s_barrier()
;     __device__ __forceinline__ void operator()(f32x4 (&acc)[2][2][4][2], const Unit& u, int wr, int wc, int fr, int fq) const {
;     ...
;             for (int m = 0; m < 4; ++m) { const int r = ai * HALF + wr * 64 + m * 16 + fr; const f32x4 s4 = *(const PG8_LAS f32x4*)(xch + 1024 + r * 4);
;                 const float inv = 1.0f / ((s4[0] + s4[1]) + (s4[2] + s4[3]));
;                 bf16_t* rowp = P + (size_t)(u.pm >> 5) * bgap + (size_t)(u.pm * BM + r) * 1024 + u.pn * BM + wc * 32 + 8 * fq;
; #pragma unroll
;                 for (int bj = 0; bj < 2; ++bj) { const f32x4 v0 = acc[ai][bj][m][0] * inv, v1 = acc[ai][bj][m][1] * inv;
;                     u32x4 w; w.x = cvt_pk_bf16(v0[0], v0[1]); w.y = cvt_pk_bf16(v0[2], v0[3]); w.z = cvt_pk_bf16(v1[0], v1[1]); w.w = cvt_pk_bf16(v1[2], v1[3]);
;                     *(u32x4*)(rowp + bj * HALF) = w; }
;                 asm volatile("" ::: "memory"); }
; template <class Epi, class Sched, bool ALIGN_EPI = false, bool SP2 = false>
; __device__ __forceinline__ void gemm_phase(PG8_LAS unsigned char* lds, const Gemm g, const Sched& S, const Epi& E, int wave_in) {
;     ...
;         if constexpr (!Epi::AFTER_DRAIN) { E(acc, cur, wr, wc, fr, fq); S.done(cur); }
;         if (!has_next) break;
; #pragma unroll
;         for (int a = 0; a < 2; ++a)
; #pragma unroll
;             for (int b = 0; b < 2; ++b)
; #pragma unroll
;                 for (int m = 0; m < 4; ++m)
; #pragma unroll
;                     for (int n = 0; n < 2; ++n) acc[a][b][m][n] = (f32x4){0.f, 0.f, 0.f, 0.f};
;         cur = nxt; cA = nA; cB = nB; ++ui;
;         if constexpr (ALIGN_EPI) { if (wr == 1) PG8_BAR; }
	v_mov_b32_e32 v36, v29
	v_mov_b32_e32 v37, v30
	v_mov_b32_e32 v29, v31
	v_pk_add_f32 v[28:29], v[36:37], v[28:29]
	s_nop 0
	v_add_f32_e32 v28, v28, v29
	v_div_scale_f32 v29, s[26:27], v28, v28, 1.0
	v_rcp_f32_e32 v30, v29
	s_nop 0
	v_fma_f32 v31, -v29, v30, 1.0
	v_fmac_f32_e32 v30, v31, v30
	v_div_scale_f32 v31, vcc, 1.0, v28, 1.0
	v_mul_f32_e32 v36, v31, v30
	v_fma_f32 v37, -v29, v36, v31
	v_fmac_f32_e32 v36, v37, v30
	v_fma_f32 v29, -v29, v36, v31
	v_div_fmas_f32 v29, v29, v30, v36
	v_div_fixup_f32 v30, v29, v28, 1.0
	v_add_u32_e32 v28, s13, v221
	v_ashrrev_i32_e32 v29, 31, v28
	v_lshlrev_b64 v[28:29], 11, v[28:29]
	v_lshl_add_u64 v[28:29], s[22:23], 0, v[28:29]
	v_lshl_add_u64 v[28:29], v[28:29], 0, s[24:25]
	v_lshl_add_u64 v[28:29], v[28:29], 0, s[86:87]
	v_pk_mul_f32 v[14:15], v[14:15], v[30:31] op_sel_hi:[1,0]
	v_lshl_add_u64 v[36:37], v[28:29], 0, v[192:193]
	v_pk_mul_f32 v[28:29], v[26:27], v[30:31] op_sel_hi:[1,0]
	v_pk_mul_f32 v[20:21], v[20:21], v[30:31] op_sel_hi:[1,0]
	v_cvt_pk_bf16_f32 v26, v14, v15
	v_pk_mul_f32 v[14:15], v[24:25], v[30:31] op_sel_hi:[1,0]
	v_pk_mul_f32 v[12:13], v[12:13], v[30:31] op_sel_hi:[1,0]
	v_pk_mul_f32 v[32:33], v[32:33], v[30:31] op_sel_hi:[1,0]
	v_cvt_pk_bf16_f32 v27, v28, v29
	v_cvt_pk_bf16_f32 v28, v20, v21
	v_pk_mul_f32 v[20:21], v[34:35], v[30:31] op_sel_hi:[1,0]
	v_cvt_pk_bf16_f32 v29, v32, v33
	global_store_dwordx4 v[36:37], v[26:29], off nt
	v_pk_mul_f32 v[22:23], v[22:23], v[30:31] op_sel_hi:[1,0]
	v_cvt_pk_bf16_f32 v12, v12, v13
	v_cvt_pk_bf16_f32 v13, v14, v15
	s_nop 0
	v_cvt_pk_bf16_f32 v14, v22, v23
	v_cvt_pk_bf16_f32 v15, v20, v21
	global_store_dwordx4 v[36:37], v[12:15], off offset:256 nt
	ds_read_b128 v[12:15], v233
	s_waitcnt lgkmcnt(0)
	v_mov_b32_e32 v20, v13
	v_mov_b32_e32 v21, v14
	v_mov_b32_e32 v13, v15
	v_pk_add_f32 v[12:13], v[20:21], v[12:13]
	s_nop 0
	v_add_f32_e32 v12, v12, v13
	v_div_scale_f32 v13, s[26:27], v12, v12, 1.0
	v_rcp_f32_e32 v14, v13
	s_nop 0
	v_fma_f32 v15, -v13, v14, 1.0
	v_fmac_f32_e32 v14, v15, v14
	v_div_scale_f32 v15, vcc, 1.0, v12, 1.0
	v_mul_f32_e32 v20, v15, v14
	v_fma_f32 v21, -v13, v20, v15
	v_fmac_f32_e32 v20, v21, v14
	v_fma_f32 v13, -v13, v20, v15
	v_div_fmas_f32 v13, v13, v14, v20
	v_add_u32_e32 v14, s13, v222
	v_ashrrev_i32_e32 v15, 31, v14
	v_lshlrev_b64 v[14:15], 11, v[14:15]
	v_lshl_add_u64 v[14:15], s[22:23], 0, v[14:15]
	v_div_fixup_f32 v12, v13, v12, 1.0
	v_lshl_add_u64 v[14:15], v[14:15], 0, s[24:25]
	v_lshl_add_u64 v[14:15], v[14:15], 0, s[86:87]
	v_pk_mul_f32 v[2:3], v[2:3], v[12:13] op_sel_hi:[1,0]
	v_lshl_add_u64 v[14:15], v[14:15], 0, v[192:193]
	v_pk_mul_f32 v[10:11], v[10:11], v[12:13] op_sel_hi:[1,0]
	v_pk_mul_f32 v[4:5], v[4:5], v[12:13] op_sel_hi:[1,0]
	v_cvt_pk_bf16_f32 v2, v2, v3
	v_cvt_pk_bf16_f32 v3, v10, v11
	v_pk_mul_f32 v[16:17], v[16:17], v[12:13] op_sel_hi:[1,0]
	v_cvt_pk_bf16_f32 v4, v4, v5
	v_pk_mul_f32 v[0:1], v[0:1], v[12:13] op_sel_hi:[1,0]
	v_cvt_pk_bf16_f32 v5, v16, v17
	global_store_dwordx4 v[14:15], v[2:5], off nt
	v_pk_mul_f32 v[6:7], v[6:7], v[12:13] op_sel_hi:[1,0]
	v_cvt_pk_bf16_f32 v0, v0, v1
	s_andn2_b64 vcc, exec, s[42:43]
	v_pk_mul_f32 v[2:3], v[8:9], v[12:13] op_sel_hi:[1,0]
	v_pk_mul_f32 v[4:5], v[18:19], v[12:13] op_sel_hi:[1,0]
	v_cvt_pk_bf16_f32 v1, v2, v3
	v_cvt_pk_bf16_f32 v2, v6, v7
	s_mov_b64 s[22:23], -1
	v_cvt_pk_bf16_f32 v3, v4, v5
	global_store_dwordx4 v[14:15], v[0:3], off offset:256 nt
	s_cbranch_vccnz .LBB0_679
	s_andn2_b64 vcc, exec, s[0:1]
	s_cbranch_vccnz .LBB0_678
	s_barrier
	s_branch .LBB0_678
